# GEMM output tiles that go through the LDS store path (in-proj Z, up-proj U, merge M) stored write-through (sc1)
# speedup vs baseline: 1.0054x; 1.0045x over previous
;     DEVINL bf16_t* Wup() const { return (bf16_t*)(ws + OFF_WUP); }
;     DEVINL bf16_t* H() const { return (bf16_t*)(ws + OFF_RW); }
; template <int NI>
; DEVINL void gemm_kloop(const bf16_t* __restrict__ A, int lda, const bf16_t* __restrict__ Bt, int ldb, int K, int m0, int n0,
;                        unsigned char* lds, f32x16 (&acc)[NI][2]) {
;     ...
;     const int nt = K >> 6;
;     asm volatile("s_waitcnt lgkmcnt(0)" ::: "memory");
;     __builtin_amdgcn_s_barrier();
;     GEMM_ISSUE(0, 0);
;     if (nt > 1) GEMM_ISSUE(1, 1);
;     const int sw = (r >> 1) & 7;
;     int o4[4];
; #pragma unroll
;     for (int ks = 0; ks < 4; ++ks) o4[ks] = ((ks * 2 + h) ^ sw) * 16;
;     int cur = 0;
;     auto compute = [&](int st_) {
;         const unsigned char* pa = lds + st_ * STAGE + (wm * 64 + r) * 128;
;         const unsigned char* pb = lds + st_ * STAGE + A_ST + (wn * 32 * NI + r) * 128;
;         bf16x8 af[2][2], bfr[2][NI];
; #pragma unroll
;         for (int i = 0; i < 2; ++i) af[0][i] = *(const bf16x8*)(pa + i * 32 * 128 + o4[0]);
; DEVINL void phase_up(const Ctx& c, unsigned char* lds) {
;     ...
;     for (int q = slot; q < (halves ? nfull : total); q += G) {
;         int tm, tn; tile_of(q, MT, NT, tm, tn);
;         f32x16 acc[2][2]; zero_acc(acc);
;         gemm_kloop(c.H(), DM, c.Wup(), DM, DM, tm * 256, tn * 128, lds, acc);
.LBB0_45:
	s_mul_hi_i32 s1, s0, 0x78787879
	s_lshr_b32 s4, s1, 31
	s_ashr_i32 s1, s1, 8
	s_add_i32 s1, s1, s4
	s_mul_i32 s4, s1, 0xfffffde0
	s_add_i32 s4, s0, s4
	s_ashr_i32 s5, s4, 31
	s_lshr_b32 s5, s5, 29
	s_add_i32 s5, s4, s5
	s_and_b32 s6, s5, 0x1fffff8
	s_sub_i32 s6, s4, s6
	s_lshl_b32 s4, s5, 5
	v_mov_b32_e32 v4, v160
	s_and_b32 s4, s4, 0xffffff00
	s_lshl_b32 s1, s1, 10
	v_ashrrev_i32_e32 v2, 3, v4
	v_lshrrev_b32_e32 v0, 4, v4
	v_xor_b32_e32 v3, v0, v4
	v_add_u32_e32 v0, s4, v2
	v_ashrrev_i32_e32 v1, 31, v0
	s_lshl_b32 s5, s6, 7
	v_lshlrev_b64 v[0:1], 11, v[0:1]
	v_lshlrev_b32_e32 v3, 4, v3
	v_lshl_add_u32 v89, v4, 4, 0
	s_add_i32 s1, s5, s1
	v_lshl_add_u64 v[0:1], s[22:23], 0, v[0:1]
	v_and_b32_e32 v64, 0x70, v3
	v_readfirstlane_b32 s14, v89
	v_add_u32_e32 v92, 0x2000, v89
	v_lshl_add_u64 v[74:75], v[0:1], 0, v[64:65]
	v_add_u32_e32 v0, s1, v2
	s_mov_b32 m0, s14
	v_readfirstlane_b32 s13, v92
	v_add_u32_e32 v91, 0x4000, v89
	v_ashrrev_i32_e32 v1, 31, v0
	s_waitcnt lgkmcnt(0)
	s_barrier
	global_load_lds_dwordx4 v[74:75], off
	v_lshl_add_u64 v[2:3], v[74:75], 0, s[68:69]
	s_mov_b32 m0, s13
	v_readfirstlane_b32 s12, v91
	v_add_u32_e32 v90, 0x6000, v89
	v_lshlrev_b64 v[0:1], 11, v[0:1]
	v_add_u32_e32 v88, 0x8000, v89
	global_load_lds_dwordx4 v[2:3], off
	v_lshl_add_u64 v[2:3], v[74:75], 0, s[10:11]
	s_mov_b32 m0, s12
	v_readfirstlane_b32 s11, v90
	v_lshl_add_u64 v[0:1], s[30:31], 0, v[0:1]
	global_load_lds_dwordx4 v[2:3], off
	v_lshl_add_u64 v[2:3], v[74:75], 0, s[8:9]
	s_mov_b32 m0, s11
	v_readfirstlane_b32 s10, v88
	v_add_u32_e32 v87, 0xa000, v89
	global_load_lds_dwordx4 v[2:3], off
	v_lshl_add_u64 v[76:77], v[0:1], 0, v[64:65]
	s_mov_b32 m0, s10
	v_readfirstlane_b32 s9, v87
	v_add_u32_e32 v99, 0xc000, v89
	global_load_lds_dwordx4 v[76:77], off
	v_lshl_add_u64 v[0:1], v[76:77], 0, s[68:69]
	s_mov_b32 m0, s9
	v_readfirstlane_b32 s16, v99
	v_add_u32_e32 v97, 0xe000, v89
	global_load_lds_dwordx4 v[0:1], off
	v_lshl_add_u64 v[0:1], v[74:75], 0, s[92:93]
	s_mov_b32 m0, s16
	v_readfirstlane_b32 s15, v97
	v_add_u32_e32 v2, 0x10000, v89
	global_load_lds_dwordx4 v[0:1], off
	v_lshl_add_u64 v[0:1], v[74:75], 0, s[60:61]
	s_mov_b32 m0, s15
	v_readfirstlane_b32 s8, v2
	v_add_u32_e32 v2, 0x12000, v89
	global_load_lds_dwordx4 v[0:1], off
	v_lshl_add_u64 v[0:1], v[74:75], 0, s[18:19]
	s_mov_b32 m0, s8
	v_readfirstlane_b32 s7, v2
	v_add_u32_e32 v2, 0x14000, v89
	global_load_lds_dwordx4 v[0:1], off
	v_lshl_add_u64 v[0:1], v[74:75], 0, s[20:21]
	s_mov_b32 m0, s7
	v_readfirstlane_b32 s6, v2
	v_add_u32_e32 v2, 0x16000, v89
	global_load_lds_dwordx4 v[0:1], off
	v_lshl_add_u64 v[0:1], v[76:77], 0, s[92:93]
	s_mov_b32 m0, s6
	v_readfirstlane_b32 s5, v2
	global_load_lds_dwordx4 v[0:1], off
	v_lshl_add_u64 v[0:1], v[76:77], 0, s[60:61]
	s_mov_b32 m0, s5
	v_bfe_u32 v2, v4, 1, 3
	global_load_lds_dwordx4 v[0:1], off
	v_lshrrev_b32_e32 v0, 5, v4
	v_bfe_u32 v1, v4, 5, 1
	v_bitop3_b32 v3, v1, v2, 6 bitop3:0x36
	v_bitop3_b32 v0, v0, v2, 1 bitop3:0x6c
	v_lshlrev_b32_e32 v96, 4, v3
	v_bitop3_b32 v3, v1, v2, 4 bitop3:0x36
	v_bitop3_b32 v1, v1, v2, 2 bitop3:0x36
	v_lshlrev_b32_e32 v106, 4, v0
	v_lshlrev_b32_e32 v0, 7, v4
	v_add_u32_e32 v100, 0x18000, v89
	v_lshlrev_b32_e32 v105, 4, v1
	v_and_b32_e32 v1, 0xf80, v0
	v_and_b32_e32 v108, 0x6f80, v0
	v_lshlrev_b32_e32 v0, 5, v4
	v_readfirstlane_b32 s19, v100
	v_add_u32_e32 v101, 0x1a000, v89
	v_and_or_b32 v107, v0, s35, v1
	v_lshl_add_u64 v[0:1], v[74:75], 0, s[84:85]
	s_mov_b32 m0, s19
	v_readfirstlane_b32 s18, v101
	v_add_u32_e32 v102, 0x1c000, v89
	s_waitcnt vmcnt(6)
	s_barrier
	global_load_lds_dwordx4 v[0:1], off
	v_lshl_add_u64 v[0:1], v[74:75], 0, s[24:25]
	s_mov_b32 m0, s18
	v_readfirstlane_b32 s20, v102
	v_add_u32_e32 v103, 0x1e000, v89
	global_load_lds_dwordx4 v[0:1], off
	v_lshl_add_u64 v[0:1], v[74:75], 0, s[26:27]
	s_mov_b32 m0, s20
	s_mov_b64 s[24:25], 0x60100
	v_readfirstlane_b32 s21, v103
	v_add_u32_e32 v104, 0x20000, v89
	global_load_lds_dwordx4 v[0:1], off
	v_lshl_add_u64 v[0:1], v[74:75], 0, s[24:25]
	s_mov_b32 m0, s21
	v_readfirstlane_b32 s24, v104
	v_add_u32_e32 v98, 0x22000, v89
	global_load_lds_dwordx4 v[0:1], off
	v_lshl_add_u64 v[0:1], v[76:77], 0, s[84:85]
	s_mov_b64 s[26:27], 0x20100
	s_mov_b32 m0, s24
	v_readfirstlane_b32 s17, v98
	global_load_lds_dwordx4 v[0:1], off
	v_lshl_add_u64 v[0:1], v[76:77], 0, s[26:27]
	s_mov_b32 m0, s17
	v_add_u32_e32 v85, 0, v108
	v_add_u32_e32 v86, 0, v107
	global_load_lds_dwordx4 v[0:1], off
	v_add_u32_e32 v80, v85, v106
	v_add_u32_e32 v64, v86, v106
	v_lshlrev_b32_e32 v95, 4, v3
	ds_read_b128 v[4:7], v80
	ds_read_b128 v[0:3], v80 offset:4096
	ds_read_b128 v[8:11], v64 offset:32768
	ds_read_b128 v[12:15], v64 offset:36864
	s_waitcnt lgkmcnt(0)
	v_mfma_f32_32x32x16_bf16 v[48:63], v[8:11], v[4:7], 0
	v_add_u32_e32 v81, v85, v105
	v_add_u32_e32 v82, v86, v105
	ds_read_b128 v[66:69], v81
	ds_read_b128 v[70:73], v81 offset:4096
	ds_read_b128 v[110:113], v82 offset:32768
	ds_read_b128 v[114:117], v82 offset:36864
	v_add_u32_e32 v83, v85, v95
	v_add_u32_e32 v84, v86, v95
	ds_read_b128 v[118:121], v83
	ds_read_b128 v[122:125], v83 offset:4096
	v_mfma_f32_32x32x16_bf16 v[32:47], v[12:15], v[4:7], 0
	ds_read_b128 v[126:129], v84 offset:32768
	ds_read_b128 v[130:133], v84 offset:36864
	v_add_u32_e32 v85, v85, v96
	v_add_u32_e32 v86, v86, v96
	s_mov_b32 m0, s14
	s_mov_b64 s[96:97], 0x60180
	s_add_i32 s25, 0, 0x14000
	v_add_u32_e32 v109, s25, v107
	v_mfma_f32_32x32x16_bf16 v[16:31], v[8:11], v[0:3], 0
	v_add_u32_e32 v93, v109, v106
	v_add_u32_e32 v94, v109, v105
	s_mov_b64 s[62:63], 0x40200
	s_mov_b64 s[90:91], 0x60200
	s_add_i32 s25, 0, 0x18000
	v_add_u32_e32 v140, s25, v108
	v_add_u32_e32 v141, s42, v107
	v_mfma_f32_32x32x16_bf16 v[0:15], v[12:15], v[0:3], 0
	s_mov_b64 s[72:73], 0x40280
	s_mov_b64 s[50:51], 0x60280
	s_mov_b64 s[36:37], 0x20400
	s_mov_b64 s[52:53], 0x40680
	s_add_i32 s0, s0, s70
	s_mov_b64 s[26:27], 0x40100
	s_cmp_ge_i32 s0, s34
	s_waitcnt lgkmcnt(0)
	v_mfma_f32_32x32x16_bf16 v[48:63], v[110:113], v[66:69], v[48:63]
	v_mfma_f32_32x32x16_bf16 v[32:47], v[114:117], v[66:69], v[32:47]
	v_mfma_f32_32x32x16_bf16 v[0:15], v[114:117], v[70:73], v[0:15]
	v_mfma_f32_32x32x16_bf16 v[16:31], v[110:113], v[70:73], v[16:31]
	ds_read_b128 v[66:69], v85
	ds_read_b128 v[70:73], v85 offset:4096
	ds_read_b128 v[110:113], v86 offset:32768
	ds_read_b128 v[114:117], v86 offset:36864
	s_waitcnt vmcnt(6)
	s_barrier
; #define MFMA32(a, b, c) __builtin_amdgcn_mfma_f32_32x32x16_bf16((a), (b), (c), 0, 0, 0)
; template <int NI>
; DEVINL void gemm_kloop(const bf16_t* __restrict__ A, int lda, const bf16_t* __restrict__ Bt, int ldb, int K, int m0, int n0,
;                        unsigned char* lds, f32x16 (&acc)[NI][2]) {
;     ...
;         for (int ks = 0; ks < 4; ++ks) {
;             if (ks < 3) {
; #pragma unroll
;                 for (int i = 0; i < 2; ++i) af[(ks + 1) & 1][i] = *(const bf16x8*)(pa + i * 32 * 128 + o4[ks + 1]);
; #pragma unroll
;                 for (int i = 0; i < NI; ++i) bfr[(ks + 1) & 1][i] = *(const bf16x8*)(pb + i * 32 * 128 + o4[ks + 1]);
;             }
; #pragma unroll
;             for (int ni = 0; ni < NI; ++ni)
; #pragma unroll
;                 for (int mi = 0; mi < 2; ++mi) acc[ni][mi] = MFMA32(bfr[ks & 1][ni], af[ks & 1][mi], acc[ni][mi]);
;         }
;     };
;     int t = 0;
;     for (; t + 2 < nt; ++t) {
;         if (NI == 2) asm volatile("s_waitcnt vmcnt(6)" ::: "memory"); else asm volatile("s_waitcnt vmcnt(5)" ::: "memory");
;         __builtin_amdgcn_s_barrier();
;         { const int s2 = (cur >= 1) ? cur - 1 : 2; GEMM_ISSUE(s2, t + 2); }
;         compute(cur);
;         cur = (cur == 2) ? 0 : cur + 1;
;     }
	v_mfma_f32_32x32x16_bf16 v[48:63], v[126:129], v[118:121], v[48:63]
	v_mfma_f32_32x32x16_bf16 v[32:47], v[130:133], v[118:121], v[32:47]
	v_mfma_f32_32x32x16_bf16 v[0:15], v[130:133], v[122:125], v[0:15]
	v_mfma_f32_32x32x16_bf16 v[16:31], v[126:129], v[122:125], v[16:31]
	s_waitcnt lgkmcnt(0)
	v_mfma_f32_32x32x16_bf16 v[48:63], v[110:113], v[66:69], v[48:63]
	v_mfma_f32_32x32x16_bf16 v[32:47], v[114:117], v[66:69], v[32:47]
	v_lshl_add_u64 v[66:67], v[74:75], 0, s[88:89]
	global_load_lds_dwordx4 v[66:67], off
	v_lshl_add_u64 v[66:67], v[74:75], 0, s[56:57]
	s_mov_b32 m0, s13
	s_mov_b64 s[56:57], 0x40180
	global_load_lds_dwordx4 v[66:67], off
	v_lshl_add_u64 v[66:67], v[74:75], 0, s[56:57]
	s_mov_b32 m0, s12
	v_mfma_f32_32x32x16_bf16 v[0:15], v[114:117], v[70:73], v[0:15]
	global_load_lds_dwordx4 v[66:67], off
	v_lshl_add_u64 v[66:67], v[74:75], 0, s[96:97]
	s_mov_b32 m0, s11
	s_mov_b64 s[56:57], 0x20180
	global_load_lds_dwordx4 v[66:67], off
	v_lshl_add_u64 v[66:67], v[76:77], 0, s[88:89]
	s_mov_b32 m0, s10
	v_mfma_f32_32x32x16_bf16 v[16:31], v[110:113], v[70:73], v[16:31]
	global_load_lds_dwordx4 v[66:67], off
	v_lshl_add_u64 v[66:67], v[76:77], 0, s[56:57]
	s_mov_b32 m0, s9
	s_mov_b64 s[96:97], 0x20200
	global_load_lds_dwordx4 v[66:67], off
	ds_read_b128 v[70:73], v80 offset:49152
	ds_read_b128 v[66:69], v80 offset:53248
	ds_read_b128 v[110:113], v93
	ds_read_b128 v[114:117], v93 offset:4096
	ds_read_b128 v[118:121], v81 offset:49152
	ds_read_b128 v[122:125], v81 offset:53248
	s_waitcnt lgkmcnt(0)
	v_mfma_f32_32x32x16_bf16 v[0:15], v[114:117], v[66:69], v[0:15]
	ds_read_b128 v[126:129], v94
	ds_read_b128 v[130:133], v94 offset:4096
	s_mov_b32 m0, s16
	v_mfma_f32_32x32x16_bf16 v[48:63], v[110:113], v[70:73], v[48:63]
	v_mfma_f32_32x32x16_bf16 v[16:31], v[110:113], v[66:69], v[16:31]
	v_add_u32_e32 v66, v109, v95
	v_add_u32_e32 v67, v109, v96
	v_mfma_f32_32x32x16_bf16 v[32:47], v[114:117], v[70:73], v[32:47]
	ds_read_b128 v[68:71], v83 offset:49152
	ds_read_b128 v[110:113], v83 offset:53248
	ds_read_b128 v[114:117], v66
	ds_read_b128 v[134:137], v66 offset:4096
	v_add_u32_e32 v72, v140, v95
	v_add_u32_e32 v73, v141, v95
	v_add_u32_e32 v95, v140, v96
	v_add_u32_e32 v96, v141, v96
	s_waitcnt lgkmcnt(0)
	v_mfma_f32_32x32x16_bf16 v[0:15], v[130:133], v[122:125], v[0:15]
	v_mfma_f32_32x32x16_bf16 v[48:63], v[126:129], v[118:121], v[48:63]
	v_mfma_f32_32x32x16_bf16 v[16:31], v[126:129], v[122:125], v[16:31]
	v_mfma_f32_32x32x16_bf16 v[32:47], v[130:133], v[118:121], v[32:47]
	ds_read_b128 v[118:121], v85 offset:49152
	ds_read_b128 v[122:125], v85 offset:53248
	ds_read_b128 v[126:129], v67
	ds_read_b128 v[130:133], v67 offset:4096
	s_waitcnt vmcnt(6)
	s_barrier
	v_mfma_f32_32x32x16_bf16 v[0:15], v[134:137], v[110:113], v[0:15]
	v_mfma_f32_32x32x16_bf16 v[48:63], v[114:117], v[68:71], v[48:63]
	v_mfma_f32_32x32x16_bf16 v[16:31], v[114:117], v[110:113], v[16:31]
	v_mfma_f32_32x32x16_bf16 v[32:47], v[134:137], v[68:71], v[32:47]
	v_lshl_add_u64 v[68:69], v[74:75], 0, s[58:59]
	global_load_lds_dwordx4 v[68:69], off
	v_lshl_add_u64 v[68:69], v[74:75], 0, s[96:97]
	s_mov_b32 m0, s15
	v_add_u32_e32 v70, v140, v105
	global_load_lds_dwordx4 v[68:69], off
	v_lshl_add_u64 v[68:69], v[74:75], 0, s[62:63]
	s_mov_b32 m0, s8
	s_waitcnt lgkmcnt(0)
	v_mfma_f32_32x32x16_bf16 v[0:15], v[130:133], v[122:125], v[0:15]
	global_load_lds_dwordx4 v[68:69], off
	v_lshl_add_u64 v[68:69], v[74:75], 0, s[90:91]
	s_mov_b32 m0, s7
	v_add_u32_e32 v71, v141, v105
	global_load_lds_dwordx4 v[68:69], off
	v_lshl_add_u64 v[68:69], v[76:77], 0, s[58:59]
	s_mov_b32 m0, s6
	v_mfma_f32_32x32x16_bf16 v[48:63], v[126:129], v[118:121], v[48:63]
	global_load_lds_dwordx4 v[68:69], off
	v_lshl_add_u64 v[68:69], v[76:77], 0, s[96:97]
	s_mov_b32 m0, s5
	s_mov_b64 s[62:63], 0x20280
	global_load_lds_dwordx4 v[68:69], off
	v_add_u32_e32 v68, v140, v106
	v_add_u32_e32 v69, v141, v106
	v_mfma_f32_32x32x16_bf16 v[16:31], v[126:129], v[122:125], v[16:31]
	ds_read_b128 v[108:111], v68
	ds_read_b128 v[112:115], v68 offset:4096
	s_mov_b32 m0, s19
	s_mov_b64 s[90:91], 0x20300
	v_mfma_f32_32x32x16_bf16 v[32:47], v[130:133], v[118:121], v[32:47]
	ds_read_b128 v[116:119], v69
	ds_read_b128 v[120:123], v69 offset:4096
	ds_read_b128 v[124:127], v70
	ds_read_b128 v[128:131], v70 offset:4096
	ds_read_b128 v[132:135], v71
	ds_read_b128 v[136:139], v71 offset:4096
	s_waitcnt lgkmcnt(0)
	v_mfma_f32_32x32x16_bf16 v[0:15], v[120:123], v[112:115], v[0:15]
	v_mfma_f32_32x32x16_bf16 v[48:63], v[116:119], v[108:111], v[48:63]
	v_mfma_f32_32x32x16_bf16 v[16:31], v[116:119], v[112:115], v[16:31]
	v_mfma_f32_32x32x16_bf16 v[32:47], v[120:123], v[108:111], v[32:47]
	ds_read_b128 v[106:109], v72
	ds_read_b128 v[110:113], v72 offset:4096
	ds_read_b128 v[114:117], v73
	ds_read_b128 v[118:121], v73 offset:4096
	v_mfma_f32_32x32x16_bf16 v[0:15], v[136:139], v[128:131], v[0:15]
	v_mfma_f32_32x32x16_bf16 v[48:63], v[132:135], v[124:127], v[48:63]
	v_mfma_f32_32x32x16_bf16 v[16:31], v[132:135], v[128:131], v[16:31]
	v_mfma_f32_32x32x16_bf16 v[32:47], v[136:139], v[124:127], v[32:47]
	ds_read_b128 v[122:125], v95
	ds_read_b128 v[126:129], v95 offset:4096
	ds_read_b128 v[130:133], v96
	ds_read_b128 v[134:137], v96 offset:4096
	s_waitcnt vmcnt(6)
	s_barrier
; #define MFMA32(a, b, c) __builtin_amdgcn_mfma_f32_32x32x16_bf16((a), (b), (c), 0, 0, 0)
; template <int NI>
; DEVINL void gemm_kloop(const bf16_t* __restrict__ A, int lda, const bf16_t* __restrict__ Bt, int ldb, int K, int m0, int n0,
;                        unsigned char* lds, f32x16 (&acc)[NI][2]) {
;     ...
;         for (int ks = 0; ks < 4; ++ks) {
;             if (ks < 3) {
; #pragma unroll
;                 for (int i = 0; i < 2; ++i) af[(ks + 1) & 1][i] = *(const bf16x8*)(pa + i * 32 * 128 + o4[ks + 1]);
; #pragma unroll
;                 for (int i = 0; i < NI; ++i) bfr[(ks + 1) & 1][i] = *(const bf16x8*)(pb + i * 32 * 128 + o4[ks + 1]);
;             }
; #pragma unroll
;             for (int ni = 0; ni < NI; ++ni)
; #pragma unroll
;                 for (int mi = 0; mi < 2; ++mi) acc[ni][mi] = MFMA32(bfr[ks & 1][ni], af[ks & 1][mi], acc[ni][mi]);
;         }
;     };
;     int t = 0;
;     for (; t + 2 < nt; ++t) {
;         if (NI == 2) asm volatile("s_waitcnt vmcnt(6)" ::: "memory"); else asm volatile("s_waitcnt vmcnt(5)" ::: "memory");
;         __builtin_amdgcn_s_barrier();
;         { const int s2 = (cur >= 1) ? cur - 1 : 2; GEMM_ISSUE(s2, t + 2); }
;         compute(cur);
;         cur = (cur == 2) ? 0 : cur + 1;
;     }
	s_waitcnt lgkmcnt(0)
	v_mfma_f32_32x32x16_bf16 v[0:15], v[118:121], v[110:113], v[0:15]
	v_mfma_f32_32x32x16_bf16 v[48:63], v[114:117], v[106:109], v[48:63]
	v_mfma_f32_32x32x16_bf16 v[16:31], v[114:117], v[110:113], v[16:31]
	v_mfma_f32_32x32x16_bf16 v[32:47], v[118:121], v[106:109], v[32:47]
	v_lshl_add_u64 v[106:107], v[74:75], 0, s[64:65]
	global_load_lds_dwordx4 v[106:107], off
	v_lshl_add_u64 v[106:107], v[74:75], 0, s[62:63]
	s_mov_b32 m0, s18
	s_nop 0
	global_load_lds_dwordx4 v[106:107], off
	v_mfma_f32_32x32x16_bf16 v[0:15], v[134:137], v[126:129], v[0:15]
	v_lshl_add_u64 v[106:107], v[74:75], 0, s[72:73]
	s_mov_b32 m0, s20
	s_mov_b64 s[72:73], 0x20380
	global_load_lds_dwordx4 v[106:107], off
	v_lshl_add_u64 v[106:107], v[74:75], 0, s[50:51]
	s_mov_b32 m0, s21
	v_mfma_f32_32x32x16_bf16 v[48:63], v[130:133], v[122:125], v[48:63]
	global_load_lds_dwordx4 v[106:107], off
	v_lshl_add_u64 v[106:107], v[76:77], 0, s[64:65]
	s_mov_b32 m0, s24
	s_mov_b64 s[50:51], 0x40300
	global_load_lds_dwordx4 v[106:107], off
	v_lshl_add_u64 v[106:107], v[76:77], 0, s[62:63]
	s_mov_b32 m0, s17
	v_mfma_f32_32x32x16_bf16 v[16:31], v[130:133], v[126:129], v[16:31]
	global_load_lds_dwordx4 v[106:107], off
	s_mov_b32 m0, s14
	v_mfma_f32_32x32x16_bf16 v[32:47], v[134:137], v[122:125], v[32:47]
	ds_read_b128 v[106:109], v80
	ds_read_b128 v[110:113], v80 offset:4096
	ds_read_b128 v[114:117], v64 offset:32768
	ds_read_b128 v[118:121], v64 offset:36864
	ds_read_b128 v[122:125], v81
	ds_read_b128 v[126:129], v81 offset:4096
	ds_read_b128 v[130:133], v82 offset:32768
	ds_read_b128 v[134:137], v82 offset:36864
	s_waitcnt lgkmcnt(0)
	v_mfma_f32_32x32x16_bf16 v[0:15], v[118:121], v[110:113], v[0:15]
	v_mfma_f32_32x32x16_bf16 v[48:63], v[114:117], v[106:109], v[48:63]
	v_mfma_f32_32x32x16_bf16 v[16:31], v[114:117], v[110:113], v[16:31]
	v_mfma_f32_32x32x16_bf16 v[32:47], v[118:121], v[106:109], v[32:47]
	ds_read_b128 v[106:109], v83
	ds_read_b128 v[110:113], v83 offset:4096
	ds_read_b128 v[114:117], v84 offset:32768
	ds_read_b128 v[118:121], v84 offset:36864
	v_mfma_f32_32x32x16_bf16 v[0:15], v[134:137], v[126:129], v[0:15]
	v_mfma_f32_32x32x16_bf16 v[48:63], v[130:133], v[122:125], v[48:63]
	v_mfma_f32_32x32x16_bf16 v[16:31], v[130:133], v[126:129], v[16:31]
	v_mfma_f32_32x32x16_bf16 v[32:47], v[134:137], v[122:125], v[32:47]
	ds_read_b128 v[122:125], v85
	ds_read_b128 v[126:129], v85 offset:4096
	ds_read_b128 v[130:133], v86 offset:32768
	ds_read_b128 v[134:137], v86 offset:36864
	s_waitcnt vmcnt(6)
	s_barrier
	s_waitcnt lgkmcnt(0)
	v_mfma_f32_32x32x16_bf16 v[0:15], v[118:121], v[110:113], v[0:15]
	v_mfma_f32_32x32x16_bf16 v[48:63], v[114:117], v[106:109], v[48:63]
	v_mfma_f32_32x32x16_bf16 v[16:31], v[114:117], v[110:113], v[16:31]
	v_mfma_f32_32x32x16_bf16 v[32:47], v[118:121], v[106:109], v[32:47]
	v_lshl_add_u64 v[106:107], v[74:75], 0, s[2:3]
	global_load_lds_dwordx4 v[106:107], off
	v_lshl_add_u64 v[106:107], v[74:75], 0, s[90:91]
	s_mov_b32 m0, s13
	s_nop 0
	global_load_lds_dwordx4 v[106:107], off
	v_mfma_f32_32x32x16_bf16 v[0:15], v[134:137], v[126:129], v[0:15]
	v_lshl_add_u64 v[106:107], v[74:75], 0, s[50:51]
	s_mov_b64 s[50:51], 0x60300
	s_mov_b32 m0, s12
	s_nop 0
	global_load_lds_dwordx4 v[106:107], off
	v_lshl_add_u64 v[106:107], v[74:75], 0, s[50:51]
	s_mov_b32 m0, s11
	v_mfma_f32_32x32x16_bf16 v[48:63], v[130:133], v[122:125], v[48:63]
	global_load_lds_dwordx4 v[106:107], off
	v_lshl_add_u64 v[106:107], v[76:77], 0, s[2:3]
	s_mov_b32 m0, s10
	s_mov_b64 s[50:51], 0x40380
	global_load_lds_dwordx4 v[106:107], off
	v_lshl_add_u64 v[106:107], v[76:77], 0, s[90:91]
	s_mov_b32 m0, s9
	v_mfma_f32_32x32x16_bf16 v[16:31], v[130:133], v[126:129], v[16:31]
	global_load_lds_dwordx4 v[106:107], off
	s_mov_b32 m0, s16
	v_mfma_f32_32x32x16_bf16 v[32:47], v[134:137], v[122:125], v[32:47]
	ds_read_b128 v[106:109], v80 offset:49152
	ds_read_b128 v[110:113], v80 offset:53248
	ds_read_b128 v[114:117], v93
	ds_read_b128 v[118:121], v93 offset:4096
	ds_read_b128 v[122:125], v81 offset:49152
	ds_read_b128 v[126:129], v81 offset:53248
	ds_read_b128 v[130:133], v94
	ds_read_b128 v[134:137], v94 offset:4096
	s_waitcnt lgkmcnt(0)
	v_mfma_f32_32x32x16_bf16 v[0:15], v[118:121], v[110:113], v[0:15]
	v_mfma_f32_32x32x16_bf16 v[48:63], v[114:117], v[106:109], v[48:63]
	v_mfma_f32_32x32x16_bf16 v[16:31], v[114:117], v[110:113], v[16:31]
	v_mfma_f32_32x32x16_bf16 v[32:47], v[118:121], v[106:109], v[32:47]
	ds_read_b128 v[106:109], v83 offset:49152
	ds_read_b128 v[110:113], v83 offset:53248
	ds_read_b128 v[114:117], v66
	ds_read_b128 v[118:121], v66 offset:4096
	v_mfma_f32_32x32x16_bf16 v[0:15], v[134:137], v[126:129], v[0:15]
	v_mfma_f32_32x32x16_bf16 v[48:63], v[130:133], v[122:125], v[48:63]
	v_mfma_f32_32x32x16_bf16 v[16:31], v[130:133], v[126:129], v[16:31]
	v_mfma_f32_32x32x16_bf16 v[32:47], v[134:137], v[122:125], v[32:47]
	ds_read_b128 v[122:125], v85 offset:49152
	ds_read_b128 v[126:129], v85 offset:53248
	ds_read_b128 v[130:133], v67
	ds_read_b128 v[134:137], v67 offset:4096
	s_waitcnt vmcnt(6)
	s_barrier
; #define MFMA32(a, b, c) __builtin_amdgcn_mfma_f32_32x32x16_bf16((a), (b), (c), 0, 0, 0)
; template <int NI>
; DEVINL void gemm_kloop(const bf16_t* __restrict__ A, int lda, const bf16_t* __restrict__ Bt, int ldb, int K, int m0, int n0,
;                        unsigned char* lds, f32x16 (&acc)[NI][2]) {
;     ...
;         for (int ks = 0; ks < 4; ++ks) {
;             if (ks < 3) {
; #pragma unroll
;                 for (int i = 0; i < 2; ++i) af[(ks + 1) & 1][i] = *(const bf16x8*)(pa + i * 32 * 128 + o4[ks + 1]);
; #pragma unroll
;                 for (int i = 0; i < NI; ++i) bfr[(ks + 1) & 1][i] = *(const bf16x8*)(pb + i * 32 * 128 + o4[ks + 1]);
;             }
; #pragma unroll
;             for (int ni = 0; ni < NI; ++ni)
; #pragma unroll
;                 for (int mi = 0; mi < 2; ++mi) acc[ni][mi] = MFMA32(bfr[ks & 1][ni], af[ks & 1][mi], acc[ni][mi]);
;         }
;     };
;     int t = 0;
;     for (; t + 2 < nt; ++t) {
;         if (NI == 2) asm volatile("s_waitcnt vmcnt(6)" ::: "memory"); else asm volatile("s_waitcnt vmcnt(5)" ::: "memory");
;         __builtin_amdgcn_s_barrier();
;         { const int s2 = (cur >= 1) ? cur - 1 : 2; GEMM_ISSUE(s2, t + 2); }
;         compute(cur);
;         cur = (cur == 2) ? 0 : cur + 1;
;     }
	s_waitcnt lgkmcnt(0)
	v_mfma_f32_32x32x16_bf16 v[0:15], v[118:121], v[110:113], v[0:15]
	v_mfma_f32_32x32x16_bf16 v[48:63], v[114:117], v[106:109], v[48:63]
	v_mfma_f32_32x32x16_bf16 v[16:31], v[114:117], v[110:113], v[16:31]
	v_mfma_f32_32x32x16_bf16 v[32:47], v[118:121], v[106:109], v[32:47]
	v_lshl_add_u64 v[106:107], v[74:75], 0, s[40:41]
	global_load_lds_dwordx4 v[106:107], off
	v_lshl_add_u64 v[106:107], v[74:75], 0, s[72:73]
	s_mov_b32 m0, s15
	s_nop 0
	global_load_lds_dwordx4 v[106:107], off
	v_mfma_f32_32x32x16_bf16 v[0:15], v[134:137], v[126:129], v[0:15]
	v_lshl_add_u64 v[106:107], v[74:75], 0, s[50:51]
	s_mov_b64 s[50:51], 0x60380
	s_mov_b32 m0, s8
	s_nop 0
	global_load_lds_dwordx4 v[106:107], off
	v_lshl_add_u64 v[106:107], v[74:75], 0, s[50:51]
	s_mov_b32 m0, s7
	v_mfma_f32_32x32x16_bf16 v[48:63], v[130:133], v[122:125], v[48:63]
	global_load_lds_dwordx4 v[106:107], off
	v_lshl_add_u64 v[106:107], v[76:77], 0, s[40:41]
	s_mov_b32 m0, s6
	s_mov_b64 s[50:51], 0x400
	global_load_lds_dwordx4 v[106:107], off
	v_lshl_add_u64 v[106:107], v[76:77], 0, s[72:73]
	s_mov_b32 m0, s5
	v_mfma_f32_32x32x16_bf16 v[16:31], v[130:133], v[126:129], v[16:31]
	global_load_lds_dwordx4 v[106:107], off
	s_mov_b32 m0, s19
	v_mfma_f32_32x32x16_bf16 v[32:47], v[134:137], v[122:125], v[32:47]
	ds_read_b128 v[106:109], v68
	ds_read_b128 v[110:113], v68 offset:4096
	ds_read_b128 v[114:117], v69
	ds_read_b128 v[118:121], v69 offset:4096
	ds_read_b128 v[122:125], v70
	ds_read_b128 v[126:129], v70 offset:4096
	ds_read_b128 v[130:133], v71
	ds_read_b128 v[134:137], v71 offset:4096
	s_waitcnt lgkmcnt(0)
	v_mfma_f32_32x32x16_bf16 v[0:15], v[118:121], v[110:113], v[0:15]
	v_mfma_f32_32x32x16_bf16 v[48:63], v[114:117], v[106:109], v[48:63]
	v_mfma_f32_32x32x16_bf16 v[16:31], v[114:117], v[110:113], v[16:31]
	v_mfma_f32_32x32x16_bf16 v[32:47], v[118:121], v[106:109], v[32:47]
	ds_read_b128 v[106:109], v72
	ds_read_b128 v[110:113], v72 offset:4096
	ds_read_b128 v[114:117], v73
	ds_read_b128 v[118:121], v73 offset:4096
	v_mfma_f32_32x32x16_bf16 v[0:15], v[134:137], v[126:129], v[0:15]
	v_mfma_f32_32x32x16_bf16 v[48:63], v[130:133], v[122:125], v[48:63]
	v_mfma_f32_32x32x16_bf16 v[16:31], v[130:133], v[126:129], v[16:31]
	v_mfma_f32_32x32x16_bf16 v[32:47], v[134:137], v[122:125], v[32:47]
	ds_read_b128 v[122:125], v95
	ds_read_b128 v[126:129], v95 offset:4096
	ds_read_b128 v[130:133], v96
	ds_read_b128 v[134:137], v96 offset:4096
	s_waitcnt vmcnt(6)
	s_barrier
	s_waitcnt lgkmcnt(0)
	v_mfma_f32_32x32x16_bf16 v[0:15], v[118:121], v[110:113], v[0:15]
	v_mfma_f32_32x32x16_bf16 v[48:63], v[114:117], v[106:109], v[48:63]
	v_mfma_f32_32x32x16_bf16 v[16:31], v[114:117], v[110:113], v[16:31]
	v_mfma_f32_32x32x16_bf16 v[32:47], v[118:121], v[106:109], v[32:47]
	v_lshl_add_u64 v[106:107], v[74:75], 0, s[50:51]
	global_load_lds_dwordx4 v[106:107], off
	v_lshl_add_u64 v[106:107], v[74:75], 0, s[36:37]
	s_mov_b64 s[36:37], 0x40400
	s_mov_b32 m0, s18
	s_mov_b64 s[18:19], 0x60400
	v_mfma_f32_32x32x16_bf16 v[0:15], v[134:137], v[126:129], v[0:15]
	global_load_lds_dwordx4 v[106:107], off
	v_lshl_add_u64 v[106:107], v[74:75], 0, s[36:37]
	s_mov_b32 m0, s20
	s_mov_b64 s[36:37], 0x480
	global_load_lds_dwordx4 v[106:107], off
	v_lshl_add_u64 v[106:107], v[74:75], 0, s[18:19]
	s_mov_b32 m0, s21
	s_mov_b64 s[18:19], 0x20400
	global_load_lds_dwordx4 v[106:107], off
	v_lshl_add_u64 v[106:107], v[76:77], 0, s[50:51]
	s_mov_b32 m0, s24
	v_mfma_f32_32x32x16_bf16 v[48:63], v[130:133], v[122:125], v[48:63]
	global_load_lds_dwordx4 v[106:107], off
	v_lshl_add_u64 v[106:107], v[76:77], 0, s[18:19]
	s_mov_b32 m0, s17
	s_mov_b64 s[20:21], 0x20480
	global_load_lds_dwordx4 v[106:107], off
	v_mfma_f32_32x32x16_bf16 v[16:31], v[130:133], v[126:129], v[16:31]
	s_mov_b32 m0, s14
	s_mov_b64 s[50:51], 0x40480
	s_mov_b64 s[14:15], 0x60480
	s_mov_b64 s[16:17], 0x40500
	s_mov_b64 s[18:19], 0x60500
	s_mov_b64 s[24:25], 0x580
	v_mfma_f32_32x32x16_bf16 v[32:47], v[134:137], v[122:125], v[32:47]
	ds_read_b128 v[106:109], v80
	ds_read_b128 v[110:113], v80 offset:4096
	ds_read_b128 v[114:117], v64 offset:32768
	ds_read_b128 v[118:121], v64 offset:36864
	ds_read_b128 v[122:125], v81
	ds_read_b128 v[126:129], v81 offset:4096
	ds_read_b128 v[130:133], v82 offset:32768
	ds_read_b128 v[134:137], v82 offset:36864
	s_waitcnt lgkmcnt(0)
	v_mfma_f32_32x32x16_bf16 v[0:15], v[118:121], v[110:113], v[0:15]
	v_mfma_f32_32x32x16_bf16 v[48:63], v[114:117], v[106:109], v[48:63]
	v_mfma_f32_32x32x16_bf16 v[16:31], v[114:117], v[110:113], v[16:31]
	v_mfma_f32_32x32x16_bf16 v[32:47], v[118:121], v[106:109], v[32:47]
	ds_read_b128 v[106:109], v83
	ds_read_b128 v[110:113], v83 offset:4096
	ds_read_b128 v[114:117], v84 offset:32768
	ds_read_b128 v[118:121], v84 offset:36864
	v_mfma_f32_32x32x16_bf16 v[0:15], v[134:137], v[126:129], v[0:15]
	v_mfma_f32_32x32x16_bf16 v[48:63], v[130:133], v[122:125], v[48:63]
	v_mfma_f32_32x32x16_bf16 v[16:31], v[130:133], v[126:129], v[16:31]
	v_mfma_f32_32x32x16_bf16 v[32:47], v[134:137], v[122:125], v[32:47]
	ds_read_b128 v[122:125], v85
	ds_read_b128 v[126:129], v85 offset:4096
	ds_read_b128 v[130:133], v86 offset:32768
	ds_read_b128 v[134:137], v86 offset:36864
	s_waitcnt vmcnt(6)
	s_barrier
; #define MFMA32(a, b, c) __builtin_amdgcn_mfma_f32_32x32x16_bf16((a), (b), (c), 0, 0, 0)
; template <int NI>
; DEVINL void gemm_kloop(const bf16_t* __restrict__ A, int lda, const bf16_t* __restrict__ Bt, int ldb, int K, int m0, int n0,
;                        unsigned char* lds, f32x16 (&acc)[NI][2]) {
;     ...
;         for (int ks = 0; ks < 4; ++ks) {
;             if (ks < 3) {
; #pragma unroll
;                 for (int i = 0; i < 2; ++i) af[(ks + 1) & 1][i] = *(const bf16x8*)(pa + i * 32 * 128 + o4[ks + 1]);
; #pragma unroll
;                 for (int i = 0; i < NI; ++i) bfr[(ks + 1) & 1][i] = *(const bf16x8*)(pb + i * 32 * 128 + o4[ks + 1]);
;             }
; #pragma unroll
;             for (int ni = 0; ni < NI; ++ni)
; #pragma unroll
;                 for (int mi = 0; mi < 2; ++mi) acc[ni][mi] = MFMA32(bfr[ks & 1][ni], af[ks & 1][mi], acc[ni][mi]);
;         }
;     };
;     int t = 0;
;     for (; t + 2 < nt; ++t) {
;         if (NI == 2) asm volatile("s_waitcnt vmcnt(6)" ::: "memory"); else asm volatile("s_waitcnt vmcnt(5)" ::: "memory");
;         __builtin_amdgcn_s_barrier();
;         { const int s2 = (cur >= 1) ? cur - 1 : 2; GEMM_ISSUE(s2, t + 2); }
;         compute(cur);
;         cur = (cur == 2) ? 0 : cur + 1;
;     }
	s_waitcnt lgkmcnt(0)
	v_mfma_f32_32x32x16_bf16 v[0:15], v[118:121], v[110:113], v[0:15]
	v_mfma_f32_32x32x16_bf16 v[48:63], v[114:117], v[106:109], v[48:63]
	v_mfma_f32_32x32x16_bf16 v[16:31], v[114:117], v[110:113], v[16:31]
	v_mfma_f32_32x32x16_bf16 v[32:47], v[118:121], v[106:109], v[32:47]
	v_lshl_add_u64 v[106:107], v[74:75], 0, s[36:37]
	global_load_lds_dwordx4 v[106:107], off
	v_lshl_add_u64 v[106:107], v[74:75], 0, s[20:21]
	s_mov_b32 m0, s13
	s_nop 0
	global_load_lds_dwordx4 v[106:107], off
	v_mfma_f32_32x32x16_bf16 v[0:15], v[134:137], v[126:129], v[0:15]
	v_lshl_add_u64 v[106:107], v[74:75], 0, s[50:51]
	s_mov_b32 m0, s12
	s_mov_b64 s[12:13], 0x500
	global_load_lds_dwordx4 v[106:107], off
	v_lshl_add_u64 v[106:107], v[74:75], 0, s[14:15]
	s_mov_b32 m0, s11
	v_mfma_f32_32x32x16_bf16 v[48:63], v[130:133], v[122:125], v[48:63]
	global_load_lds_dwordx4 v[106:107], off
	v_lshl_add_u64 v[106:107], v[76:77], 0, s[36:37]
	s_mov_b32 m0, s10
	v_readfirstlane_b32 s10, v99
	global_load_lds_dwordx4 v[106:107], off
	v_lshl_add_u64 v[106:107], v[76:77], 0, s[20:21]
	s_mov_b32 m0, s9
	v_mfma_f32_32x32x16_bf16 v[16:31], v[130:133], v[126:129], v[16:31]
	global_load_lds_dwordx4 v[106:107], off
	s_mov_b64 s[14:15], 0x20500
	s_mov_b32 m0, s10
	v_readfirstlane_b32 s9, v97
	s_mov_b64 s[36:37], 0x20580
	v_readfirstlane_b32 s11, v101
	v_mfma_f32_32x32x16_bf16 v[32:47], v[134:137], v[122:125], v[32:47]
	ds_read_b128 v[106:109], v80 offset:49152
	ds_read_b128 v[110:113], v80 offset:53248
	ds_read_b128 v[114:117], v93
	ds_read_b128 v[118:121], v93 offset:4096
	ds_read_b128 v[122:125], v81 offset:49152
	ds_read_b128 v[126:129], v81 offset:53248
	ds_read_b128 v[130:133], v94
	ds_read_b128 v[134:137], v94 offset:4096
	s_mov_b64 s[50:51], 0x40580
	v_readfirstlane_b32 s20, v98
	v_readfirstlane_b32 s21, v89
	s_waitcnt lgkmcnt(0)
	v_mfma_f32_32x32x16_bf16 v[0:15], v[118:121], v[110:113], v[0:15]
	v_mfma_f32_32x32x16_bf16 v[48:63], v[114:117], v[106:109], v[48:63]
	v_mfma_f32_32x32x16_bf16 v[16:31], v[114:117], v[110:113], v[16:31]
	v_mfma_f32_32x32x16_bf16 v[32:47], v[118:121], v[106:109], v[32:47]
	ds_read_b128 v[106:109], v83 offset:49152
	ds_read_b128 v[110:113], v83 offset:53248
	ds_read_b128 v[114:117], v66
	ds_read_b128 v[118:121], v66 offset:4096
	v_mfma_f32_32x32x16_bf16 v[0:15], v[134:137], v[126:129], v[0:15]
	v_mfma_f32_32x32x16_bf16 v[48:63], v[130:133], v[122:125], v[48:63]
	v_mfma_f32_32x32x16_bf16 v[16:31], v[130:133], v[126:129], v[16:31]
	v_mfma_f32_32x32x16_bf16 v[32:47], v[134:137], v[122:125], v[32:47]
	ds_read_b128 v[122:125], v85 offset:49152
	ds_read_b128 v[126:129], v85 offset:53248
	ds_read_b128 v[130:133], v67
	ds_read_b128 v[134:137], v67 offset:4096
	s_waitcnt vmcnt(6)
	s_barrier
	s_waitcnt lgkmcnt(0)
	v_mfma_f32_32x32x16_bf16 v[0:15], v[118:121], v[110:113], v[0:15]
	v_mfma_f32_32x32x16_bf16 v[48:63], v[114:117], v[106:109], v[48:63]
	v_mfma_f32_32x32x16_bf16 v[16:31], v[114:117], v[110:113], v[16:31]
	v_mfma_f32_32x32x16_bf16 v[32:47], v[118:121], v[106:109], v[32:47]
	v_lshl_add_u64 v[106:107], v[74:75], 0, s[12:13]
	global_load_lds_dwordx4 v[106:107], off
	v_lshl_add_u64 v[106:107], v[74:75], 0, s[14:15]
	s_mov_b32 m0, s9
	s_nop 0
	global_load_lds_dwordx4 v[106:107], off
	v_mfma_f32_32x32x16_bf16 v[0:15], v[134:137], v[126:129], v[0:15]
	v_lshl_add_u64 v[106:107], v[74:75], 0, s[16:17]
	s_mov_b32 m0, s8
	s_mov_b64 s[16:17], 0x60580
	global_load_lds_dwordx4 v[106:107], off
	v_lshl_add_u64 v[106:107], v[74:75], 0, s[18:19]
	s_mov_b32 m0, s7
	v_mfma_f32_32x32x16_bf16 v[48:63], v[130:133], v[122:125], v[48:63]
	global_load_lds_dwordx4 v[106:107], off
	v_lshl_add_u64 v[106:107], v[76:77], 0, s[12:13]
	s_mov_b32 m0, s6
	v_readfirstlane_b32 s12, v102
	global_load_lds_dwordx4 v[106:107], off
	v_lshl_add_u64 v[106:107], v[76:77], 0, s[14:15]
	s_mov_b32 m0, s5
	v_mfma_f32_32x32x16_bf16 v[16:31], v[130:133], v[126:129], v[16:31]
	global_load_lds_dwordx4 v[106:107], off
	v_readfirstlane_b32 s15, v100
	s_mov_b32 m0, s15
	v_lshl_add_u64 v[100:101], v[74:75], 0, s[50:51]
	v_readfirstlane_b32 s13, v103
	v_readfirstlane_b32 s14, v104
	v_mfma_f32_32x32x16_bf16 v[32:47], v[134:137], v[122:125], v[32:47]
	ds_read_b128 v[106:109], v68
	ds_read_b128 v[110:113], v68 offset:4096
	ds_read_b128 v[114:117], v69
	ds_read_b128 v[118:121], v69 offset:4096
	ds_read_b128 v[122:125], v70
	ds_read_b128 v[126:129], v70 offset:4096
	ds_read_b128 v[130:133], v71
	ds_read_b128 v[134:137], v71 offset:4096
	s_mov_b64 s[18:19], 0x40600
	s_mov_b64 s[50:51], 0x60600
	s_waitcnt lgkmcnt(0)
	v_mfma_f32_32x32x16_bf16 v[0:15], v[118:121], v[110:113], v[0:15]
	v_mfma_f32_32x32x16_bf16 v[48:63], v[114:117], v[106:109], v[48:63]
	v_mfma_f32_32x32x16_bf16 v[16:31], v[114:117], v[110:113], v[16:31]
	v_mfma_f32_32x32x16_bf16 v[32:47], v[118:121], v[106:109], v[32:47]
	ds_read_b128 v[106:109], v72
	ds_read_b128 v[110:113], v72 offset:4096
	ds_read_b128 v[114:117], v73
	ds_read_b128 v[118:121], v73 offset:4096
	v_mfma_f32_32x32x16_bf16 v[0:15], v[134:137], v[126:129], v[0:15]
	v_mfma_f32_32x32x16_bf16 v[48:63], v[130:133], v[122:125], v[48:63]
	v_mfma_f32_32x32x16_bf16 v[16:31], v[130:133], v[126:129], v[16:31]
	v_mfma_f32_32x32x16_bf16 v[32:47], v[134:137], v[122:125], v[32:47]
	ds_read_b128 v[122:125], v95
	ds_read_b128 v[126:129], v95 offset:4096
	ds_read_b128 v[130:133], v96
	ds_read_b128 v[134:137], v96 offset:4096
	s_waitcnt vmcnt(6)
	s_barrier
; #define MFMA32(a, b, c) __builtin_amdgcn_mfma_f32_32x32x16_bf16((a), (b), (c), 0, 0, 0)
; template <int NI>
; DEVINL void gemm_kloop(const bf16_t* __restrict__ A, int lda, const bf16_t* __restrict__ Bt, int ldb, int K, int m0, int n0,
;                        unsigned char* lds, f32x16 (&acc)[NI][2]) {
;     ...
;         for (int ks = 0; ks < 4; ++ks) {
;             if (ks < 3) {
; #pragma unroll
;                 for (int i = 0; i < 2; ++i) af[(ks + 1) & 1][i] = *(const bf16x8*)(pa + i * 32 * 128 + o4[ks + 1]);
; #pragma unroll
;                 for (int i = 0; i < NI; ++i) bfr[(ks + 1) & 1][i] = *(const bf16x8*)(pb + i * 32 * 128 + o4[ks + 1]);
;             }
; #pragma unroll
;             for (int ni = 0; ni < NI; ++ni)
; #pragma unroll
;                 for (int mi = 0; mi < 2; ++mi) acc[ni][mi] = MFMA32(bfr[ks & 1][ni], af[ks & 1][mi], acc[ni][mi]);
;         }
;     };
;     int t = 0;
;     for (; t + 2 < nt; ++t) {
;         if (NI == 2) asm volatile("s_waitcnt vmcnt(6)" ::: "memory"); else asm volatile("s_waitcnt vmcnt(5)" ::: "memory");
;         __builtin_amdgcn_s_barrier();
;         { const int s2 = (cur >= 1) ? cur - 1 : 2; GEMM_ISSUE(s2, t + 2); }
;         compute(cur);
;         cur = (cur == 2) ? 0 : cur + 1;
;     }
	s_waitcnt lgkmcnt(0)
	v_mfma_f32_32x32x16_bf16 v[0:15], v[118:121], v[110:113], v[0:15]
	v_mfma_f32_32x32x16_bf16 v[48:63], v[114:117], v[106:109], v[48:63]
	v_mfma_f32_32x32x16_bf16 v[16:31], v[114:117], v[110:113], v[16:31]
	v_mfma_f32_32x32x16_bf16 v[32:47], v[118:121], v[106:109], v[32:47]
	v_lshl_add_u64 v[106:107], v[74:75], 0, s[24:25]
	global_load_lds_dwordx4 v[106:107], off
	v_lshl_add_u64 v[106:107], v[74:75], 0, s[36:37]
	s_mov_b32 m0, s11
	s_nop 0
	global_load_lds_dwordx4 v[106:107], off
	v_mfma_f32_32x32x16_bf16 v[0:15], v[134:137], v[126:129], v[0:15]
	s_mov_b32 m0, s12
	s_nop 0
	global_load_lds_dwordx4 v[100:101], off
	v_lshl_add_u64 v[100:101], v[74:75], 0, s[16:17]
	s_mov_b32 m0, s13
	v_readfirstlane_b32 s16, v92
	global_load_lds_dwordx4 v[100:101], off
	v_lshl_add_u64 v[100:101], v[76:77], 0, s[24:25]
	s_mov_b32 m0, s14
	v_mfma_f32_32x32x16_bf16 v[48:63], v[130:133], v[122:125], v[48:63]
	global_load_lds_dwordx4 v[100:101], off
	v_lshl_add_u64 v[100:101], v[76:77], 0, s[36:37]
	s_mov_b32 m0, s20
	s_mov_b64 s[24:25], 0x600
	global_load_lds_dwordx4 v[100:101], off
	v_mfma_f32_32x32x16_bf16 v[16:31], v[130:133], v[126:129], v[16:31]
	s_mov_b64 s[36:37], 0x20600
	s_mov_b32 m0, s21
	v_readfirstlane_b32 s17, v91
	v_mfma_f32_32x32x16_bf16 v[32:47], v[134:137], v[122:125], v[32:47]
	ds_read_b128 v[98:101], v80
	ds_read_b128 v[102:105], v80 offset:4096
	ds_read_b128 v[106:109], v64 offset:32768
	ds_read_b128 v[110:113], v64 offset:36864
	ds_read_b128 v[114:117], v81
	ds_read_b128 v[118:121], v81 offset:4096
	ds_read_b128 v[122:125], v82 offset:32768
	ds_read_b128 v[126:129], v82 offset:36864
	s_waitcnt lgkmcnt(0)
	v_mfma_f32_32x32x16_bf16 v[0:15], v[110:113], v[102:105], v[0:15]
	v_mfma_f32_32x32x16_bf16 v[48:63], v[106:109], v[98:101], v[48:63]
	v_mfma_f32_32x32x16_bf16 v[16:31], v[106:109], v[102:105], v[16:31]
	v_mfma_f32_32x32x16_bf16 v[32:47], v[110:113], v[98:101], v[32:47]
	ds_read_b128 v[98:101], v83
	ds_read_b128 v[102:105], v83 offset:4096
	ds_read_b128 v[106:109], v84 offset:32768
	ds_read_b128 v[110:113], v84 offset:36864
	v_mfma_f32_32x32x16_bf16 v[0:15], v[126:129], v[118:121], v[0:15]
	v_mfma_f32_32x32x16_bf16 v[48:63], v[122:125], v[114:117], v[48:63]
	v_mfma_f32_32x32x16_bf16 v[16:31], v[122:125], v[118:121], v[16:31]
	v_mfma_f32_32x32x16_bf16 v[32:47], v[126:129], v[114:117], v[32:47]
	ds_read_b128 v[114:117], v85
	ds_read_b128 v[118:121], v85 offset:4096
	ds_read_b128 v[122:125], v86 offset:32768
	ds_read_b128 v[126:129], v86 offset:36864
	s_waitcnt vmcnt(6)
	s_barrier
	s_waitcnt lgkmcnt(0)
	v_mfma_f32_32x32x16_bf16 v[0:15], v[110:113], v[102:105], v[0:15]
	v_mfma_f32_32x32x16_bf16 v[48:63], v[106:109], v[98:101], v[48:63]
	v_mfma_f32_32x32x16_bf16 v[16:31], v[106:109], v[102:105], v[16:31]
	v_mfma_f32_32x32x16_bf16 v[32:47], v[110:113], v[98:101], v[32:47]
	v_lshl_add_u64 v[98:99], v[74:75], 0, s[24:25]
	global_load_lds_dwordx4 v[98:99], off
	v_lshl_add_u64 v[98:99], v[74:75], 0, s[36:37]
	s_mov_b32 m0, s16
	s_nop 0
	global_load_lds_dwordx4 v[98:99], off
	v_mfma_f32_32x32x16_bf16 v[0:15], v[126:129], v[118:121], v[0:15]
	v_lshl_add_u64 v[98:99], v[74:75], 0, s[18:19]
	s_mov_b32 m0, s17
	v_readfirstlane_b32 s18, v90
	global_load_lds_dwordx4 v[98:99], off
	v_lshl_add_u64 v[98:99], v[74:75], 0, s[50:51]
	s_mov_b32 m0, s18
	v_readfirstlane_b32 s19, v88
	global_load_lds_dwordx4 v[98:99], off
	v_lshl_add_u64 v[90:91], v[76:77], 0, s[24:25]
	s_mov_b32 m0, s19
	v_readfirstlane_b32 s24, v87
	global_load_lds_dwordx4 v[90:91], off
	v_lshl_add_u64 v[88:89], v[76:77], 0, s[36:37]
	s_mov_b32 m0, s24
	v_mfma_f32_32x32x16_bf16 v[48:63], v[122:125], v[114:117], v[48:63]
	global_load_lds_dwordx4 v[88:89], off
	s_mov_b64 s[36:37], 0x680
	s_mov_b64 s[50:51], 0x20680
	s_mov_b32 m0, s10
	v_mfma_f32_32x32x16_bf16 v[16:31], v[122:125], v[118:121], v[16:31]
	v_mfma_f32_32x32x16_bf16 v[32:47], v[126:129], v[114:117], v[32:47]
	ds_read_b128 v[88:91], v80 offset:49152
	ds_read_b128 v[98:101], v80 offset:53248
	ds_read_b128 v[102:105], v93
	ds_read_b128 v[106:109], v93 offset:4096
	ds_read_b128 v[110:113], v81 offset:49152
	ds_read_b128 v[114:117], v81 offset:53248
	ds_read_b128 v[118:121], v94
	ds_read_b128 v[122:125], v94 offset:4096
	s_waitcnt lgkmcnt(0)
	v_mfma_f32_32x32x16_bf16 v[0:15], v[106:109], v[98:101], v[0:15]
	v_mfma_f32_32x32x16_bf16 v[48:63], v[102:105], v[88:91], v[48:63]
	v_mfma_f32_32x32x16_bf16 v[16:31], v[102:105], v[98:101], v[16:31]
	v_mfma_f32_32x32x16_bf16 v[32:47], v[106:109], v[88:91], v[32:47]
	ds_read_b128 v[88:91], v83 offset:49152
	ds_read_b128 v[98:101], v83 offset:53248
	ds_read_b128 v[102:105], v66
	ds_read_b128 v[106:109], v66 offset:4096
	v_mfma_f32_32x32x16_bf16 v[0:15], v[122:125], v[114:117], v[0:15]
	v_mfma_f32_32x32x16_bf16 v[48:63], v[118:121], v[110:113], v[48:63]
	v_mfma_f32_32x32x16_bf16 v[16:31], v[118:121], v[114:117], v[16:31]
	v_mfma_f32_32x32x16_bf16 v[32:47], v[122:125], v[110:113], v[32:47]
	ds_read_b128 v[110:113], v85 offset:49152
	ds_read_b128 v[114:117], v85 offset:53248
	ds_read_b128 v[118:121], v67
	ds_read_b128 v[122:125], v67 offset:4096
	s_waitcnt vmcnt(6)
	s_barrier
; #define MFMA32(a, b, c) __builtin_amdgcn_mfma_f32_32x32x16_bf16((a), (b), (c), 0, 0, 0)
; template <int NI>
; DEVINL void gemm_kloop(const bf16_t* __restrict__ A, int lda, const bf16_t* __restrict__ Bt, int ldb, int K, int m0, int n0,
;                        unsigned char* lds, f32x16 (&acc)[NI][2]) {
;     ...
;         for (int ks = 0; ks < 4; ++ks) {
;             if (ks < 3) {
; #pragma unroll
;                 for (int i = 0; i < 2; ++i) af[(ks + 1) & 1][i] = *(const bf16x8*)(pa + i * 32 * 128 + o4[ks + 1]);
; #pragma unroll
;                 for (int i = 0; i < NI; ++i) bfr[(ks + 1) & 1][i] = *(const bf16x8*)(pb + i * 32 * 128 + o4[ks + 1]);
;             }
; #pragma unroll
;             for (int ni = 0; ni < NI; ++ni)
; #pragma unroll
;                 for (int mi = 0; mi < 2; ++mi) acc[ni][mi] = MFMA32(bfr[ks & 1][ni], af[ks & 1][mi], acc[ni][mi]);
;         }
;     };
;     int t = 0;
;     for (; t + 2 < nt; ++t) {
;         if (NI == 2) asm volatile("s_waitcnt vmcnt(6)" ::: "memory"); else asm volatile("s_waitcnt vmcnt(5)" ::: "memory");
;         __builtin_amdgcn_s_barrier();
;         { const int s2 = (cur >= 1) ? cur - 1 : 2; GEMM_ISSUE(s2, t + 2); }
;         compute(cur);
;         cur = (cur == 2) ? 0 : cur + 1;
;     }
	s_waitcnt lgkmcnt(0)
	v_mfma_f32_32x32x16_bf16 v[0:15], v[106:109], v[98:101], v[0:15]
	v_mfma_f32_32x32x16_bf16 v[48:63], v[102:105], v[88:91], v[48:63]
	v_mfma_f32_32x32x16_bf16 v[16:31], v[102:105], v[98:101], v[16:31]
	v_mfma_f32_32x32x16_bf16 v[32:47], v[106:109], v[88:91], v[32:47]
	v_lshl_add_u64 v[88:89], v[74:75], 0, s[36:37]
	global_load_lds_dwordx4 v[88:89], off
	v_lshl_add_u64 v[88:89], v[74:75], 0, s[50:51]
	s_mov_b32 m0, s9
	s_nop 0
	global_load_lds_dwordx4 v[88:89], off
	v_mfma_f32_32x32x16_bf16 v[0:15], v[122:125], v[114:117], v[0:15]
	v_lshl_add_u64 v[88:89], v[74:75], 0, s[52:53]
	s_mov_b64 s[52:53], 0x60680
	s_mov_b32 m0, s8
	s_mov_b64 s[8:9], 0x60000
	global_load_lds_dwordx4 v[88:89], off
	v_lshl_add_u64 v[88:89], v[74:75], 0, s[52:53]
	s_mov_b32 m0, s7
	v_mfma_f32_32x32x16_bf16 v[48:63], v[118:121], v[110:113], v[48:63]
	global_load_lds_dwordx4 v[88:89], off
	v_lshl_add_u64 v[88:89], v[76:77], 0, s[36:37]
	s_mov_b32 m0, s6
	s_mov_b64 s[6:7], 0x700
	global_load_lds_dwordx4 v[88:89], off
	v_lshl_add_u64 v[88:89], v[76:77], 0, s[50:51]
	s_mov_b32 m0, s5
	v_mfma_f32_32x32x16_bf16 v[16:31], v[118:121], v[114:117], v[16:31]
	global_load_lds_dwordx4 v[88:89], off
	s_mov_b32 m0, s15
	s_mov_b64 s[36:37], 0x40700
	v_mfma_f32_32x32x16_bf16 v[32:47], v[122:125], v[110:113], v[32:47]
	ds_read_b128 v[88:91], v68
	ds_read_b128 v[98:101], v68 offset:4096
	ds_read_b128 v[102:105], v69
	ds_read_b128 v[106:109], v69 offset:4096
	ds_read_b128 v[110:113], v70
	ds_read_b128 v[114:117], v70 offset:4096
	ds_read_b128 v[118:121], v71
	ds_read_b128 v[122:125], v71 offset:4096
	s_waitcnt lgkmcnt(0)
	v_mfma_f32_32x32x16_bf16 v[0:15], v[106:109], v[98:101], v[0:15]
	v_mfma_f32_32x32x16_bf16 v[48:63], v[102:105], v[88:91], v[48:63]
	v_mfma_f32_32x32x16_bf16 v[16:31], v[102:105], v[98:101], v[16:31]
	v_mfma_f32_32x32x16_bf16 v[32:47], v[106:109], v[88:91], v[32:47]
	ds_read_b128 v[88:91], v72
	ds_read_b128 v[98:101], v72 offset:4096
	ds_read_b128 v[102:105], v73
	ds_read_b128 v[106:109], v73 offset:4096
	v_mfma_f32_32x32x16_bf16 v[0:15], v[122:125], v[114:117], v[0:15]
	v_mfma_f32_32x32x16_bf16 v[48:63], v[118:121], v[110:113], v[48:63]
	v_mfma_f32_32x32x16_bf16 v[16:31], v[118:121], v[114:117], v[16:31]
	v_mfma_f32_32x32x16_bf16 v[32:47], v[122:125], v[110:113], v[32:47]
	ds_read_b128 v[110:113], v95
	ds_read_b128 v[114:117], v95 offset:4096
	ds_read_b128 v[118:121], v96
	ds_read_b128 v[122:125], v96 offset:4096
	s_waitcnt vmcnt(6)
	s_barrier
	s_waitcnt lgkmcnt(0)
	v_mfma_f32_32x32x16_bf16 v[0:15], v[106:109], v[98:101], v[0:15]
	v_mfma_f32_32x32x16_bf16 v[48:63], v[102:105], v[88:91], v[48:63]
	v_mfma_f32_32x32x16_bf16 v[16:31], v[102:105], v[98:101], v[16:31]
	v_mfma_f32_32x32x16_bf16 v[32:47], v[106:109], v[88:91], v[32:47]
	v_lshl_add_u64 v[88:89], v[74:75], 0, s[6:7]
	global_load_lds_dwordx4 v[88:89], off
	v_lshl_add_u64 v[88:89], v[74:75], 0, s[54:55]
	s_mov_b32 m0, s11
	s_mov_b64 s[10:11], 0x40000
	global_load_lds_dwordx4 v[88:89], off
	v_mfma_f32_32x32x16_bf16 v[0:15], v[122:125], v[114:117], v[0:15]
	v_lshl_add_u64 v[88:89], v[74:75], 0, s[36:37]
	s_mov_b64 s[36:37], 0x60700
	s_mov_b32 m0, s12
	s_nop 0
	global_load_lds_dwordx4 v[88:89], off
	v_lshl_add_u64 v[88:89], v[74:75], 0, s[36:37]
	s_mov_b32 m0, s13
	v_mfma_f32_32x32x16_bf16 v[48:63], v[118:121], v[110:113], v[48:63]
	global_load_lds_dwordx4 v[88:89], off
	v_lshl_add_u64 v[88:89], v[76:77], 0, s[6:7]
	s_mov_b32 m0, s14
	s_mov_b64 s[6:7], 0x40780
	global_load_lds_dwordx4 v[88:89], off
	v_lshl_add_u64 v[88:89], v[76:77], 0, s[54:55]
	s_mov_b32 m0, s20
	v_mfma_f32_32x32x16_bf16 v[16:31], v[118:121], v[114:117], v[16:31]
	global_load_lds_dwordx4 v[88:89], off
	s_mov_b32 m0, s21
	s_mov_b64 s[20:21], 0x60080
	v_mfma_f32_32x32x16_bf16 v[32:47], v[122:125], v[110:113], v[32:47]
	ds_read_b128 v[88:91], v80
	ds_read_b128 v[98:101], v80 offset:4096
	ds_read_b128 v[102:105], v64 offset:32768
	ds_read_b128 v[106:109], v64 offset:36864
	ds_read_b128 v[110:113], v81
	ds_read_b128 v[114:117], v81 offset:4096
	ds_read_b128 v[118:121], v82 offset:32768
	ds_read_b128 v[122:125], v82 offset:36864
	s_waitcnt lgkmcnt(0)
	v_mfma_f32_32x32x16_bf16 v[0:15], v[106:109], v[98:101], v[0:15]
	v_mfma_f32_32x32x16_bf16 v[48:63], v[102:105], v[88:91], v[48:63]
	v_mfma_f32_32x32x16_bf16 v[16:31], v[102:105], v[98:101], v[16:31]
	v_mfma_f32_32x32x16_bf16 v[32:47], v[106:109], v[88:91], v[32:47]
	ds_read_b128 v[88:91], v83
	ds_read_b128 v[98:101], v83 offset:4096
	ds_read_b128 v[102:105], v84 offset:32768
	ds_read_b128 v[106:109], v84 offset:36864
	v_mfma_f32_32x32x16_bf16 v[0:15], v[122:125], v[114:117], v[0:15]
	v_mfma_f32_32x32x16_bf16 v[48:63], v[118:121], v[110:113], v[48:63]
	v_mfma_f32_32x32x16_bf16 v[16:31], v[118:121], v[114:117], v[16:31]
	v_mfma_f32_32x32x16_bf16 v[32:47], v[122:125], v[110:113], v[32:47]
	ds_read_b128 v[110:113], v85
	ds_read_b128 v[114:117], v85 offset:4096
	ds_read_b128 v[118:121], v86 offset:32768
	ds_read_b128 v[122:125], v86 offset:36864
	s_waitcnt vmcnt(6)
	s_barrier
; template <int NI>
; DEVINL void gemm_kloop(const bf16_t* __restrict__ A, int lda, const bf16_t* __restrict__ Bt, int ldb, int K, int m0, int n0,
;                        unsigned char* lds, f32x16 (&acc)[NI][2]) {
;     ...
;     for (; t + 2 < nt; ++t) {
;         if (NI == 2) asm volatile("s_waitcnt vmcnt(6)" ::: "memory"); else asm volatile("s_waitcnt vmcnt(5)" ::: "memory");
;         __builtin_amdgcn_s_barrier();
;         { const int s2 = (cur >= 1) ? cur - 1 : 2; GEMM_ISSUE(s2, t + 2); }
;         compute(cur);
;         cur = (cur == 2) ? 0 : cur + 1;
;     }
;     if (nt >= 2) {
;         if (NI == 2) asm volatile("s_waitcnt vmcnt(6)" ::: "memory"); else asm volatile("s_waitcnt vmcnt(5)" ::: "memory");
;         __builtin_amdgcn_s_barrier();
;         compute(cur);
;         cur = (cur == 2) ? 0 : cur + 1;
;     }
;     asm volatile("s_waitcnt vmcnt(0)" ::: "memory");
;     __builtin_amdgcn_s_barrier();
;     compute(cur);
	s_waitcnt lgkmcnt(0)
	v_mfma_f32_32x32x16_bf16 v[0:15], v[106:109], v[98:101], v[0:15]
	v_mfma_f32_32x32x16_bf16 v[48:63], v[102:105], v[88:91], v[48:63]
	v_mfma_f32_32x32x16_bf16 v[16:31], v[102:105], v[98:101], v[16:31]
	v_mfma_f32_32x32x16_bf16 v[32:47], v[106:109], v[88:91], v[32:47]
	v_lshl_add_u64 v[88:89], v[74:75], 0, vcc
	global_load_lds_dwordx4 v[88:89], off
	v_lshl_add_u64 v[88:89], v[74:75], 0, s[94:95]
	s_mov_b32 m0, s16
	s_nop 0
	global_load_lds_dwordx4 v[88:89], off
	v_mfma_f32_32x32x16_bf16 v[0:15], v[122:125], v[114:117], v[0:15]
	v_lshl_add_u64 v[88:89], v[74:75], 0, s[6:7]
	s_mov_b64 s[6:7], 0x60780
	s_mov_b32 m0, s17
	v_lshl_add_u64 v[74:75], v[74:75], 0, s[6:7]
	global_load_lds_dwordx4 v[88:89], off
	s_mov_b32 m0, s18
	v_mfma_f32_32x32x16_bf16 v[48:63], v[118:121], v[110:113], v[48:63]
	global_load_lds_dwordx4 v[74:75], off
	v_lshl_add_u64 v[74:75], v[76:77], 0, vcc
	s_mov_b32 m0, s19
	s_mov_b64 s[18:19], 0x40080
	global_load_lds_dwordx4 v[74:75], off
	v_lshl_add_u64 v[74:75], v[76:77], 0, s[94:95]
	s_mov_b32 m0, s24
	v_mfma_f32_32x32x16_bf16 v[16:31], v[118:121], v[114:117], v[16:31]
	global_load_lds_dwordx4 v[74:75], off
	s_mov_b64 s[24:25], 0x20100
	v_mfma_f32_32x32x16_bf16 v[32:47], v[122:125], v[110:113], v[32:47]
	ds_read_b128 v[74:77], v80 offset:49152
	ds_read_b128 v[88:91], v80 offset:53248
	ds_read_b128 v[98:101], v93
	ds_read_b128 v[102:105], v93 offset:4096
	ds_read_b128 v[106:109], v81 offset:49152
	ds_read_b128 v[110:113], v81 offset:53248
	ds_read_b128 v[114:117], v94
	ds_read_b128 v[118:121], v94 offset:4096
	s_waitcnt lgkmcnt(0)
	v_mfma_f32_32x32x16_bf16 v[0:15], v[102:105], v[88:91], v[0:15]
	v_mfma_f32_32x32x16_bf16 v[48:63], v[98:101], v[74:77], v[48:63]
	v_mfma_f32_32x32x16_bf16 v[16:31], v[98:101], v[88:91], v[16:31]
	v_mfma_f32_32x32x16_bf16 v[32:47], v[102:105], v[74:77], v[32:47]
	ds_read_b128 v[74:77], v83 offset:49152
	ds_read_b128 v[88:91], v83 offset:53248
	ds_read_b128 v[98:101], v66
	ds_read_b128 v[102:105], v66 offset:4096
	v_mfma_f32_32x32x16_bf16 v[0:15], v[118:121], v[110:113], v[0:15]
	v_mfma_f32_32x32x16_bf16 v[48:63], v[114:117], v[106:109], v[48:63]
	v_mfma_f32_32x32x16_bf16 v[16:31], v[114:117], v[110:113], v[16:31]
	v_mfma_f32_32x32x16_bf16 v[32:47], v[118:121], v[106:109], v[32:47]
	ds_read_b128 v[106:109], v85 offset:49152
	ds_read_b128 v[110:113], v85 offset:53248
	ds_read_b128 v[114:117], v67
	ds_read_b128 v[118:121], v67 offset:4096
	s_waitcnt vmcnt(6)
	s_barrier
	s_waitcnt lgkmcnt(0)
	v_mfma_f32_32x32x16_bf16 v[0:15], v[102:105], v[88:91], v[0:15]
	v_mfma_f32_32x32x16_bf16 v[48:63], v[98:101], v[74:77], v[48:63]
	v_mfma_f32_32x32x16_bf16 v[16:31], v[98:101], v[88:91], v[16:31]
	v_mfma_f32_32x32x16_bf16 v[32:47], v[102:105], v[74:77], v[32:47]
	v_mfma_f32_32x32x16_bf16 v[0:15], v[118:121], v[110:113], v[0:15]
	v_mfma_f32_32x32x16_bf16 v[48:63], v[114:117], v[106:109], v[48:63]
	v_mfma_f32_32x32x16_bf16 v[16:31], v[114:117], v[110:113], v[16:31]
	v_mfma_f32_32x32x16_bf16 v[32:47], v[118:121], v[106:109], v[32:47]
	ds_read_b128 v[74:77], v68
	ds_read_b128 v[88:91], v68 offset:4096
	ds_read_b128 v[98:101], v69
	ds_read_b128 v[66:69], v69 offset:4096
	ds_read_b128 v[102:105], v70
	ds_read_b128 v[106:109], v70 offset:4096
	ds_read_b128 v[110:113], v71
	ds_read_b128 v[114:117], v71 offset:4096
	s_waitcnt lgkmcnt(0)
	v_mfma_f32_32x32x16_bf16 v[0:15], v[66:69], v[88:91], v[0:15]
	v_mfma_f32_32x32x16_bf16 v[48:63], v[98:101], v[74:77], v[48:63]
	v_mfma_f32_32x32x16_bf16 v[16:31], v[98:101], v[88:91], v[16:31]
	v_mfma_f32_32x32x16_bf16 v[32:47], v[66:69], v[74:77], v[32:47]
	ds_read_b128 v[66:69], v72
	ds_read_b128 v[74:77], v72 offset:4096
	ds_read_b128 v[88:91], v73
	ds_read_b128 v[70:73], v73 offset:4096
	v_mfma_f32_32x32x16_bf16 v[0:15], v[114:117], v[106:109], v[0:15]
	v_mfma_f32_32x32x16_bf16 v[48:63], v[110:113], v[102:105], v[48:63]
	v_mfma_f32_32x32x16_bf16 v[16:31], v[110:113], v[106:109], v[16:31]
	v_mfma_f32_32x32x16_bf16 v[32:47], v[114:117], v[102:105], v[32:47]
	ds_read_b128 v[98:101], v95
	ds_read_b128 v[92:95], v95 offset:4096
	ds_read_b128 v[102:105], v96
	ds_read_b128 v[106:109], v96 offset:4096
	s_waitcnt vmcnt(0)
	s_barrier
	s_waitcnt lgkmcnt(0)
	v_mfma_f32_32x32x16_bf16 v[0:15], v[70:73], v[74:77], v[0:15]
	v_mfma_f32_32x32x16_bf16 v[48:63], v[88:91], v[66:69], v[48:63]
	v_mfma_f32_32x32x16_bf16 v[16:31], v[88:91], v[74:77], v[16:31]
	v_mfma_f32_32x32x16_bf16 v[32:47], v[70:73], v[66:69], v[32:47]
	v_mfma_f32_32x32x16_bf16 v[0:15], v[106:109], v[92:95], v[0:15]
	v_mfma_f32_32x32x16_bf16 v[48:63], v[102:105], v[98:101], v[48:63]
	v_mfma_f32_32x32x16_bf16 v[16:31], v[102:105], v[92:95], v[16:31]
	v_mfma_f32_32x32x16_bf16 v[32:47], v[106:109], v[98:101], v[32:47]
	ds_read_b128 v[66:69], v80
	ds_read_b128 v[70:73], v80 offset:4096
	ds_read_b128 v[74:77], v64 offset:32768
	ds_read_b128 v[88:91], v64 offset:36864
	ds_read_b128 v[92:95], v81
	ds_read_b128 v[96:99], v81 offset:4096
	ds_read_b128 v[100:103], v82 offset:32768
	ds_read_b128 v[104:107], v82 offset:36864
	s_waitcnt lgkmcnt(0)
	v_mfma_f32_32x32x16_bf16 v[0:15], v[88:91], v[70:73], v[0:15]
	v_mfma_f32_32x32x16_bf16 v[48:63], v[74:77], v[66:69], v[48:63]
	v_mfma_f32_32x32x16_bf16 v[32:47], v[88:91], v[66:69], v[32:47]
	v_mfma_f32_32x32x16_bf16 v[16:31], v[74:77], v[70:73], v[16:31]
	ds_read_b128 v[66:69], v83
	ds_read_b128 v[70:73], v83 offset:4096
	ds_read_b128 v[74:77], v84 offset:32768
	ds_read_b128 v[80:83], v84 offset:36864
	v_mfma_f32_32x32x16_bf16 v[0:15], v[104:107], v[96:99], v[0:15]
	v_mfma_f32_32x32x16_bf16 v[48:63], v[100:103], v[92:95], v[48:63]
	v_mfma_f32_32x32x16_bf16 v[32:47], v[104:107], v[92:95], v[32:47]
	v_mfma_f32_32x32x16_bf16 v[16:31], v[100:103], v[96:99], v[16:31]
	ds_read_b128 v[88:91], v85
	ds_read_b128 v[92:95], v85 offset:4096
	ds_read_b128 v[96:99], v86 offset:32768
	ds_read_b128 v[84:87], v86 offset:36864
	s_waitcnt lgkmcnt(0)
; DEVINL unsigned cvt_pk_bf16(float lo, float hi) { const f32x2 v = {lo, hi}; return __builtin_bit_cast(unsigned, __builtin_convertvector(v, bf16x2v)); }
; DEVINL void phase_up(const Ctx& c, unsigned char* lds) {
;     ...
;         const int mbase = tm * 256 + wm * 64, nbase = tn * 128 + wn * 64;
;         {
;             u32x2 pku[2][2][4];
; #pragma unroll
;             for (int mi = 0; mi < 2; ++mi)
; #pragma unroll
;                 for (int ni = 0; ni < 2; ++ni)
; #pragma unroll
;                     for (int g = 0; g < 4; ++g) {
;                         float v[4];
; #pragma unroll
;                         for (int j = 0; j < 4; ++j) { const float a = fmaxf(acc[ni][mi][4 * g + j], 0.f); v[j] = a * a; }
;                         pku[mi][ni][g][0] = cvt_pk_bf16(v[0], v[1]); pku[mi][ni][g][1] = cvt_pk_bf16(v[2], v[3]);
;                     }
	v_mfma_f32_32x32x16_bf16 v[0:15], v[80:83], v[70:73], v[0:15]
	v_mfma_f32_32x32x16_bf16 v[48:63], v[74:77], v[66:69], v[48:63]
	v_mfma_f32_32x32x16_bf16 v[32:47], v[80:83], v[66:69], v[32:47]
	v_or_b32_e32 v66, s4, v78
	v_ashrrev_i32_e32 v67, 31, v66
	v_mfma_f32_32x32x16_bf16 v[16:31], v[74:77], v[70:73], v[16:31]
	v_mfma_f32_32x32x16_bf16 v[0:15], v[84:87], v[92:95], v[0:15]
	v_mfma_f32_32x32x16_bf16 v[48:63], v[96:99], v[88:91], v[48:63]
	s_nop 10
	v_max_f32_e32 v0, v0, v0
	v_max_f32_e32 v1, v1, v1
	v_max_f32_e32 v2, v2, v2
	v_max_f32_e32 v3, v3, v3
	v_max_f32_e32 v0, 0, v0
	v_max_f32_e32 v1, 0, v1
	v_max_f32_e32 v2, 0, v2
	v_mfma_f32_32x32x16_bf16 v[32:47], v[84:87], v[88:91], v[32:47]
	v_max_f32_e32 v3, 0, v3
	v_mul_f32_e64 v0, v0, v0
	v_mul_f32_e64 v1, v1, v1
	v_mul_f32_e64 v2, v2, v2
	v_mul_f32_e64 v3, v3, v3
	v_cvt_pk_bf16_f32 v0, v0, v1
	v_cvt_pk_bf16_f32 v1, v2, v3
	v_max_f32_e32 v2, v4, v4
	v_max_f32_e32 v3, v5, v5
	v_mfma_f32_32x32x16_bf16 v[16:31], v[96:99], v[92:95], v[16:31]
	v_max_f32_e32 v4, v6, v6
	v_max_f32_e32 v5, v7, v7
	v_max_f32_e32 v2, 0, v2
	v_max_f32_e32 v3, 0, v3
	v_max_f32_e32 v4, 0, v4
	v_max_f32_e32 v5, 0, v5
	v_pk_mul_f32 v[2:3], v[2:3], v[2:3]
	v_pk_mul_f32 v[4:5], v[4:5], v[4:5]
	v_cvt_pk_bf16_f32 v2, v2, v3
	v_cvt_pk_bf16_f32 v3, v4, v5
	v_max_f32_e32 v4, v8, v8
	v_max_f32_e32 v5, v9, v9
	v_max_f32_e32 v6, v10, v10
	v_max_f32_e32 v7, v11, v11
	v_max_f32_e32 v48, v48, v48
	v_max_f32_e32 v49, v49, v49
	v_max_f32_e32 v50, v50, v50
	v_max_f32_e32 v51, v51, v51
	v_max_f32_e32 v32, v32, v32
	v_max_f32_e32 v33, v33, v33
	v_max_f32_e32 v34, v34, v34
	v_max_f32_e32 v35, v35, v35
	v_max_f32_e32 v4, 0, v4
	v_max_f32_e32 v5, 0, v5
	v_max_f32_e32 v6, 0, v6
	v_max_f32_e32 v7, 0, v7
	v_max_f32_e32 v48, 0, v48
	v_max_f32_e32 v49, 0, v49
	v_max_f32_e32 v50, 0, v50
	v_max_f32_e32 v51, 0, v51
	v_max_f32_e32 v32, 0, v32
	v_max_f32_e32 v33, 0, v33
	v_max_f32_e32 v34, 0, v34
	v_max_f32_e32 v35, 0, v35
	v_max_f32_e32 v16, v16, v16
	v_max_f32_e32 v17, v17, v17
	v_max_f32_e32 v18, v18, v18
	v_max_f32_e32 v19, v19, v19
	v_pk_mul_f32 v[4:5], v[4:5], v[4:5]
	v_pk_mul_f32 v[6:7], v[6:7], v[6:7]
	v_pk_mul_f32 v[48:49], v[48:49], v[48:49]
	v_pk_mul_f32 v[50:51], v[50:51], v[50:51]
	v_pk_mul_f32 v[32:33], v[32:33], v[32:33]
	v_pk_mul_f32 v[34:35], v[34:35], v[34:35]
	v_max_f32_e32 v16, 0, v16
	v_max_f32_e32 v17, 0, v17
	v_max_f32_e32 v18, 0, v18
	v_max_f32_e32 v19, 0, v19
	v_cvt_pk_bf16_f32 v4, v4, v5
	v_cvt_pk_bf16_f32 v5, v6, v7
	v_max_f32_e32 v6, v12, v12
	v_max_f32_e32 v7, v13, v13
	v_max_f32_e32 v8, v14, v14
	v_max_f32_e32 v9, v15, v15
	v_cvt_pk_bf16_f32 v48, v48, v49
	v_cvt_pk_bf16_f32 v49, v50, v51
	v_max_f32_e32 v50, v52, v52
	v_max_f32_e32 v51, v53, v53
	v_max_f32_e32 v52, v54, v54
	v_max_f32_e32 v53, v55, v55
	v_cvt_pk_bf16_f32 v32, v32, v33
	v_cvt_pk_bf16_f32 v33, v34, v35
	v_max_f32_e32 v34, v36, v36
	v_max_f32_e32 v35, v37, v37
	v_max_f32_e32 v36, v38, v38
	v_max_f32_e32 v37, v39, v39
	v_pk_mul_f32 v[16:17], v[16:17], v[16:17]
	v_pk_mul_f32 v[18:19], v[18:19], v[18:19]
	v_max_f32_e32 v6, 0, v6
	v_max_f32_e32 v7, 0, v7
	v_max_f32_e32 v8, 0, v8
	v_max_f32_e32 v9, 0, v9
	v_max_f32_e32 v50, 0, v50
	v_max_f32_e32 v51, 0, v51
	v_max_f32_e32 v52, 0, v52
	v_max_f32_e32 v53, 0, v53
	v_max_f32_e32 v34, 0, v34
	v_max_f32_e32 v35, 0, v35
	v_max_f32_e32 v36, 0, v36
	v_max_f32_e32 v37, 0, v37
	v_cvt_pk_bf16_f32 v16, v16, v17
	v_cvt_pk_bf16_f32 v17, v18, v19
	v_max_f32_e32 v18, v20, v20
	v_max_f32_e32 v19, v21, v21
	v_max_f32_e32 v20, v22, v22
	v_max_f32_e32 v21, v23, v23
	v_pk_mul_f32 v[6:7], v[6:7], v[6:7]
	v_pk_mul_f32 v[8:9], v[8:9], v[8:9]
	v_pk_mul_f32 v[50:51], v[50:51], v[50:51]
	v_pk_mul_f32 v[52:53], v[52:53], v[52:53]
	v_pk_mul_f32 v[34:35], v[34:35], v[34:35]
	v_pk_mul_f32 v[36:37], v[36:37], v[36:37]
	v_max_f32_e32 v18, 0, v18
	v_max_f32_e32 v19, 0, v19
	v_max_f32_e32 v20, 0, v20
	v_max_f32_e32 v21, 0, v21
	v_cvt_pk_bf16_f32 v6, v6, v7
	v_cvt_pk_bf16_f32 v7, v8, v9
	v_add_u32_e32 v8, s1, v79
	v_lshlrev_b64 v[10:11], 13, v[66:67]
	v_cvt_pk_bf16_f32 v50, v50, v51
	v_cvt_pk_bf16_f32 v51, v52, v53
	v_max_f32_e32 v52, v56, v56
	v_max_f32_e32 v53, v57, v57
	v_max_f32_e32 v54, v58, v58
	v_max_f32_e32 v55, v59, v59
	v_cvt_pk_bf16_f32 v34, v34, v35
	v_cvt_pk_bf16_f32 v35, v36, v37
	v_max_f32_e32 v36, v40, v40
	v_max_f32_e32 v37, v41, v41
	v_max_f32_e32 v38, v42, v42
	v_max_f32_e32 v39, v43, v43
	v_pk_mul_f32 v[18:19], v[18:19], v[18:19]
	v_pk_mul_f32 v[20:21], v[20:21], v[20:21]
	v_lshl_add_u64 v[10:11], s[28:29], 0, v[10:11]
	v_ashrrev_i32_e32 v9, 31, v8
	v_max_f32_e32 v52, 0, v52
	v_max_f32_e32 v53, 0, v53
	v_max_f32_e32 v54, 0, v54
	v_max_f32_e32 v55, 0, v55
	v_max_f32_e32 v36, 0, v36
	v_max_f32_e32 v37, 0, v37
	v_max_f32_e32 v38, 0, v38
	v_max_f32_e32 v39, 0, v39
	v_cvt_pk_bf16_f32 v18, v18, v19
	v_cvt_pk_bf16_f32 v19, v20, v21
	v_max_f32_e32 v20, v24, v24
	v_max_f32_e32 v21, v25, v25
	v_max_f32_e32 v22, v26, v26
	v_max_f32_e32 v23, v27, v27
	v_lshl_add_u64 v[8:9], v[8:9], 1, v[10:11]
	v_mov_b32_e32 v10, v160
	v_pk_mul_f32 v[52:53], v[52:53], v[52:53]
	v_pk_mul_f32 v[54:55], v[54:55], v[54:55]
	v_pk_mul_f32 v[36:37], v[36:37], v[36:37]
	v_pk_mul_f32 v[38:39], v[38:39], v[38:39]
	v_max_f32_e32 v20, 0, v20
	v_max_f32_e32 v21, 0, v21
	v_max_f32_e32 v22, 0, v22
	v_max_f32_e32 v23, 0, v23
	v_cvt_pk_bf16_f32 v52, v52, v53
	v_lshrrev_b32_e32 v11, 6, v10
	v_cvt_pk_bf16_f32 v53, v54, v55
	v_max_f32_e32 v54, v60, v60
	v_max_f32_e32 v55, v61, v61
	v_max_f32_e32 v56, v62, v62
	v_max_f32_e32 v57, v63, v63
	v_cvt_pk_bf16_f32 v36, v36, v37
	v_cvt_pk_bf16_f32 v37, v38, v39
	v_max_f32_e32 v38, v44, v44
	v_max_f32_e32 v39, v45, v45
	v_max_f32_e32 v40, v46, v46
	v_max_f32_e32 v41, v47, v47
	v_pk_mul_f32 v[20:21], v[20:21], v[20:21]
	v_pk_mul_f32 v[22:23], v[22:23], v[22:23]
	v_and_b32_e32 v12, 31, v10
	v_mul_lo_u32 v11, v11, s38
	v_lshrrev_b32_e32 v13, 2, v10
	v_max_f32_e32 v54, 0, v54
	v_max_f32_e32 v55, 0, v55
	v_max_f32_e32 v56, 0, v56
	v_max_f32_e32 v57, 0, v57
	v_max_f32_e32 v38, 0, v38
	v_max_f32_e32 v39, 0, v39
	v_max_f32_e32 v40, 0, v40
	v_max_f32_e32 v41, 0, v41
	v_cvt_pk_bf16_f32 v20, v20, v21
	v_cvt_pk_bf16_f32 v21, v22, v23
	v_max_f32_e32 v22, v28, v28
	v_max_f32_e32 v23, v29, v29
	v_max_f32_e32 v24, v30, v30
	v_max_f32_e32 v25, v31, v31
	v_add_u32_e32 v11, 0, v11
	v_mul_u32_u24_e32 v12, 0x90, v12
	v_and_b32_e32 v13, 8, v13
	v_pk_mul_f32 v[54:55], v[54:55], v[54:55]
	v_pk_mul_f32 v[56:57], v[56:57], v[56:57]
	v_pk_mul_f32 v[38:39], v[38:39], v[38:39]
	v_pk_mul_f32 v[40:41], v[40:41], v[40:41]
	v_max_f32_e32 v22, 0, v22
	v_max_f32_e32 v23, 0, v23
	v_max_f32_e32 v24, 0, v24
	v_max_f32_e32 v25, 0, v25
	v_add3_u32 v12, v11, v12, v13
	v_cvt_pk_bf16_f32 v54, v54, v55
	v_cvt_pk_bf16_f32 v55, v56, v57
	v_cvt_pk_bf16_f32 v38, v38, v39
	v_cvt_pk_bf16_f32 v39, v40, v41
	v_pk_mul_f32 v[22:23], v[22:23], v[22:23]
	v_pk_mul_f32 v[24:25], v[24:25], v[24:25]
	s_waitcnt vmcnt(0)
	s_barrier
; #define TID (opq_v((int)threadIdx.x))
; DEVINL void store_rows_via_lds(unsigned char* lds, const u32x2 (&pk)[2][2][4], bf16_t* out_row0, int ld) {
;     const int tid = TID, lane = tid & 63, w = tid >> 6, r = lane & 31, h = lane >> 5;
;     unsigned char* reg = lds + w * (64 * 144);
;     __syncthreads();
; #pragma unroll
;     for (int mi = 0; mi < 2; ++mi)
; #pragma unroll
;         for (int ni = 0; ni < 2; ++ni)
; #pragma unroll
;             for (int g = 0; g < 4; ++g) *(u32x2*)(reg + (mi * 32 + r) * 144 + (ni * 32 + 8 * g + 4 * h) * 2) = pk[mi][ni][g];
;     __syncthreads();
; #pragma unroll
;     for (int it = 0; it < 8; ++it) {
;         const int idx = it * 64 + lane, row = idx >> 3, c16 = idx & 7;
;         const u32x4 v = *(const u32x4*)(reg + row * 144 + c16 * 16);
;         *(u32x4*)(out_row0 + (size_t)row * ld + c16 * 8) = v;
;     }
; }
	ds_write2_b64 v12, v[48:49], v[50:51] offset1:2
	ds_write2_b64 v12, v[52:53], v[54:55] offset0:4 offset1:6
	ds_write2_b64 v12, v[32:33], v[34:35] offset0:8 offset1:10
	ds_write2_b64 v12, v[36:37], v[38:39] offset0:12 offset1:14
	v_add_u32_e32 v12, 0x1000, v12
	v_cvt_pk_bf16_f32 v22, v22, v23
	v_cvt_pk_bf16_f32 v23, v24, v25
	ds_write2_b64 v12, v[16:17], v[18:19] offset0:64 offset1:66
	ds_write2_b64 v12, v[20:21], v[22:23] offset0:68 offset1:70
	ds_write2_b64 v12, v[0:1], v[2:3] offset0:72 offset1:74
	ds_write2_b64 v12, v[4:5], v[6:7] offset0:76 offset1:78
	v_lshlrev_b32_e32 v0, 4, v10
	v_bfe_u32 v6, v10, 3, 3
	v_and_b32_e32 v64, 0x70, v0
	v_mul_u32_u24_e32 v2, 0x90, v6
	v_lshl_add_u64 v[0:1], v[8:9], 0, v[64:65]
	v_add3_u32 v8, v11, v64, v2
	s_waitcnt lgkmcnt(0)
	s_barrier
	ds_read_b128 v[2:5], v8
	v_lshlrev_b32_e32 v64, 13, v6
	v_lshl_add_u64 v[6:7], v[0:1], 0, v[64:65]
	s_waitcnt lgkmcnt(0)
	global_store_dwordx4 v[6:7], v[2:5], off sc1
	ds_read_b128 v[2:5], v8 offset:1152
	v_or_b32_e32 v6, 0x10000, v64
	v_mov_b32_e32 v7, v65
	v_lshl_add_u64 v[6:7], v[0:1], 0, v[6:7]
	s_waitcnt lgkmcnt(0)
	global_store_dwordx4 v[6:7], v[2:5], off sc1
	ds_read_b128 v[2:5], v8 offset:2304
	v_or_b32_e32 v6, 0x20000, v64
	v_mov_b32_e32 v7, v65
	v_lshl_add_u64 v[6:7], v[0:1], 0, v[6:7]
	s_waitcnt lgkmcnt(0)
	global_store_dwordx4 v[6:7], v[2:5], off sc1
	ds_read_b128 v[2:5], v8 offset:3456
	v_or_b32_e32 v6, 0x30000, v64
	v_mov_b32_e32 v7, v65
	v_lshl_add_u64 v[6:7], v[0:1], 0, v[6:7]
	s_waitcnt lgkmcnt(0)
	global_store_dwordx4 v[6:7], v[2:5], off sc1
	ds_read_b128 v[2:5], v8 offset:4608
	v_or_b32_e32 v6, 0x40000, v64
	v_mov_b32_e32 v7, v65
	v_lshl_add_u64 v[6:7], v[0:1], 0, v[6:7]
	s_waitcnt lgkmcnt(0)
	global_store_dwordx4 v[6:7], v[2:5], off sc1
	ds_read_b128 v[2:5], v8 offset:5760
	v_or_b32_e32 v6, 0x50000, v64
	v_mov_b32_e32 v7, v65
	v_lshl_add_u64 v[6:7], v[0:1], 0, v[6:7]
	s_waitcnt lgkmcnt(0)
	global_store_dwordx4 v[6:7], v[2:5], off sc1
	ds_read_b128 v[2:5], v8 offset:6912
	v_or_b32_e32 v6, 0x60000, v64
	v_mov_b32_e32 v7, v65
	v_lshl_add_u64 v[6:7], v[0:1], 0, v[6:7]
	v_or_b32_e32 v64, 0x70000, v64
	s_waitcnt lgkmcnt(0)
	global_store_dwordx4 v[6:7], v[2:5], off sc1
	ds_read_b128 v[2:5], v8 offset:8064
	v_lshl_add_u64 v[0:1], v[0:1], 0, v[64:65]
	s_waitcnt lgkmcnt(0)
	global_store_dwordx4 v[0:1], v[2:5], off sc1
	s_cbranch_scc0 .LBB0_45

;     DEVINL bf16_t* Pbr() const { return (bf16_t*)(ws + OFF_PBR); }
;     DEVINL bf16_t* Y() const { return (bf16_t*)(ws + OFF_Y); }
; template <int NI>
; DEVINL void gemm_kloop(const bf16_t* __restrict__ A, int lda, const bf16_t* __restrict__ Bt, int ldb, int K, int m0, int n0,
;                        unsigned char* lds, f32x16 (&acc)[NI][2]) {
;     ...
;     const int nt = K >> 6;
;     asm volatile("s_waitcnt lgkmcnt(0)" ::: "memory");
;     __builtin_amdgcn_s_barrier();
;     GEMM_ISSUE(0, 0);
;     if (nt > 1) GEMM_ISSUE(1, 1);
;     const int sw = (r >> 1) & 7;
;     int o4[4];
; #pragma unroll
;     for (int ks = 0; ks < 4; ++ks) o4[ks] = ((ks * 2 + h) ^ sw) * 16;
;     int cur = 0;
;     auto compute = [&](int st_) {
;         const unsigned char* pa = lds + st_ * STAGE + (wm * 64 + r) * 128;
;         const unsigned char* pb = lds + st_ * STAGE + A_ST + (wn * 32 * NI + r) * 128;
;         bf16x8 af[2][2], bfr[2][NI];
; #pragma unroll
;         for (int i = 0; i < 2; ++i) af[0][i] = *(const bf16x8*)(pa + i * 32 * 128 + o4[0]);
; template <int NI, int MODE>
; DEVINL void merge_tile(const Ctx& c, unsigned char* lds, int m0, int n0) {
;     ...
;     for (int bi = 0; bi < (MODE == 0 ? 3 : 1); ++bi) {
;         const int br = (MODE == 0) ? (bi == 2 ? 3 : bi) : 2;
;         f32x16 acc[NI][2]; zero_acc(acc);
;         gemm_kloop<NI>(c.Y() + (size_t)br * T * 512, 512, c.Pbr() + (size_t)br * DM * 512, 512, 512, m0, n0, lds, acc);
; DEVINL void phase_merge(const Ctx& c, unsigned char* lds) {
;     ...
;     for (int q = slot; q < (halves ? nfull : total); q += G) {
;         int tm, tn; tile_of(q, MT, NT, tm, tn);
;         merge_tile<2, 1>(c, lds, tm * 256, tn * 128);
.LBB0_89:
	s_mul_hi_i32 s4, s1, 0x78787879
	s_lshr_b32 s5, s4, 31
	s_ashr_i32 s4, s4, 8
	s_add_i32 s4, s4, s5
	s_mul_i32 s5, s4, 0xfffffde0
	s_add_i32 s5, s1, s5
	s_ashr_i32 s6, s5, 31
	s_lshr_b32 s6, s6, 29
	s_add_i32 s6, s5, s6
	s_and_b32 s7, s6, 0x1fffff8
	s_lshl_b32 s6, s6, 5
	s_waitcnt vmcnt(0)
	v_mov_b32_e32 v0, v160
	v_mov_b32_e32 v1, v160
	s_and_b32 s6, s6, 0xffffff00
	v_mov_b32_e32 v6, v160
	v_and_b32_e32 v2, 0xc0, v1
	v_or_b32_e32 v74, s6, v2
	v_and_or_b32 v75, v0, 31, v74
	v_lshrrev_b32_e32 v0, 3, v0
	v_and_b32_e32 v80, 4, v0
	v_ashrrev_i32_e32 v1, 2, v1
	v_ashrrev_i32_e32 v2, 3, v6
	v_lshrrev_b32_e32 v0, 4, v6
	v_xor_b32_e32 v3, v0, v6
	v_add_u32_e32 v0, s6, v2
	s_sub_i32 s5, s5, s7
	v_and_b32_e32 v81, 0xffffffc0, v1
	v_ashrrev_i32_e32 v1, 31, v0
	s_lshl_b32 s4, s4, 10
	s_lshl_b32 s5, s5, 7
	v_lshlrev_b64 v[0:1], 10, v[0:1]
	v_lshlrev_b32_e32 v3, 4, v3
	s_add_i32 s4, s5, s4
	v_lshl_add_u64 v[0:1], s[36:37], 0, v[0:1]
	v_and_b32_e32 v64, 0x70, v3
	v_lshl_add_u64 v[76:77], v[0:1], 0, v[64:65]
	v_add_u32_e32 v0, s4, v2
	v_ashrrev_i32_e32 v1, 31, v0
	v_lshlrev_b64 v[0:1], 10, v[0:1]
	v_lshl_add_u64 v[2:3], s[52:53], 0, v[0:1]
	v_lshl_add_u32 v0, v6, 4, 0
	v_add_u32_e32 v7, 0x2000, v0
	v_readfirstlane_b32 s16, v0
	s_mov_b32 m0, s16
	v_readfirstlane_b32 s15, v7
	v_add_u32_e32 v7, 0x4000, v0
	s_waitcnt lgkmcnt(0)
	s_barrier
	global_load_lds_dwordx4 v[76:77], off
	v_lshl_add_u64 v[4:5], v[76:77], 0, s[74:75]
	s_mov_b32 m0, s15
	v_readfirstlane_b32 s14, v7
	v_add_u32_e32 v7, 0x6000, v0
	v_add_u32_e32 v1, 0x8000, v0
	global_load_lds_dwordx4 v[4:5], off
	v_lshl_add_u64 v[4:5], v[76:77], 0, s[68:69]
	s_mov_b32 m0, s14
	s_mov_b64 s[6:7], 0x30000
	v_readfirstlane_b32 s13, v7
	global_load_lds_dwordx4 v[4:5], off
	v_lshl_add_u64 v[4:5], v[76:77], 0, s[6:7]
	s_mov_b32 m0, s13
	v_readfirstlane_b32 s12, v1
	v_add_u32_e32 v1, 0xa000, v0
	global_load_lds_dwordx4 v[4:5], off
	v_lshl_add_u64 v[78:79], v[2:3], 0, v[64:65]
	s_mov_b32 m0, s12
	v_readfirstlane_b32 s11, v1
	v_add_u32_e32 v1, 0xc000, v0
	global_load_lds_dwordx4 v[78:79], off
	v_lshl_add_u64 v[2:3], v[78:79], 0, s[74:75]
	s_mov_b32 m0, s11
	v_readfirstlane_b32 s10, v1
	v_add_u32_e32 v1, 0xe000, v0
	global_load_lds_dwordx4 v[2:3], off
	v_lshl_add_u64 v[2:3], v[76:77], 0, s[92:93]
	s_mov_b32 m0, s10
	v_readfirstlane_b32 s9, v1
	v_add_u32_e32 v1, 0x10000, v0
	global_load_lds_dwordx4 v[2:3], off
	v_lshl_add_u64 v[2:3], v[76:77], 0, s[76:77]
	s_mov_b32 m0, s9
	v_readfirstlane_b32 s8, v1
	global_load_lds_dwordx4 v[2:3], off
	v_lshl_add_u64 v[2:3], v[76:77], 0, s[60:61]
	s_mov_b32 m0, s8
	s_mov_b64 s[6:7], 0x30080
	v_add_u32_e32 v1, 0x12000, v0
	global_load_lds_dwordx4 v[2:3], off
	v_lshl_add_u64 v[2:3], v[76:77], 0, s[6:7]
	v_readfirstlane_b32 s7, v1
	v_add_u32_e32 v1, 0x14000, v0
	s_mov_b32 m0, s7
	v_readfirstlane_b32 s6, v1
	v_add_u32_e32 v1, 0x16000, v0
	global_load_lds_dwordx4 v[2:3], off
	v_lshl_add_u64 v[2:3], v[78:79], 0, s[92:93]
	s_mov_b32 m0, s6
	v_readfirstlane_b32 s5, v1
	global_load_lds_dwordx4 v[2:3], off
	v_lshl_add_u64 v[2:3], v[78:79], 0, s[76:77]
	s_mov_b32 m0, s5
	v_lshrrev_b32_e32 v1, 5, v6
	global_load_lds_dwordx4 v[2:3], off
	v_bfe_u32 v2, v6, 5, 1
	v_bfe_u32 v3, v6, 1, 3
	v_bitop3_b32 v4, v2, v3, 6 bitop3:0x36
	v_bitop3_b32 v1, v1, v3, 1 bitop3:0x6c
	v_lshlrev_b32_e32 v90, 4, v4
	v_bitop3_b32 v4, v2, v3, 4 bitop3:0x36
	v_bitop3_b32 v2, v2, v3, 2 bitop3:0x36
	v_lshlrev_b32_e32 v94, 4, v1
	v_lshlrev_b32_e32 v1, 7, v6
	v_lshlrev_b32_e32 v93, 4, v2
	v_and_b32_e32 v2, 0xf80, v1
	v_and_b32_e32 v96, 0x6f80, v1
	v_lshlrev_b32_e32 v1, 5, v6
	v_and_or_b32 v95, v1, s55, v2
	v_add_u32_e32 v1, 0x18000, v0
	v_lshl_add_u64 v[2:3], v[76:77], 0, s[84:85]
	v_readfirstlane_b32 s19, v1
	v_add_u32_e32 v1, 0x1a000, v0
	s_mov_b32 m0, s19
	v_readfirstlane_b32 s18, v1
	s_waitcnt vmcnt(6)
	s_barrier
	global_load_lds_dwordx4 v[2:3], off
	v_lshl_add_u64 v[2:3], v[76:77], 0, s[78:79]
	s_mov_b32 m0, s18
	s_mov_b64 s[20:21], 0x20100
	v_add_u32_e32 v1, 0x1c000, v0
	global_load_lds_dwordx4 v[2:3], off
	v_lshl_add_u64 v[2:3], v[76:77], 0, s[20:21]
	v_readfirstlane_b32 s20, v1
	v_add_u32_e32 v1, 0x1e000, v0
	s_mov_b32 m0, s20
	s_mov_b64 s[24:25], 0x30100
	v_readfirstlane_b32 s21, v1
	v_add_u32_e32 v1, 0x20000, v0
	global_load_lds_dwordx4 v[2:3], off
	v_lshl_add_u64 v[2:3], v[76:77], 0, s[24:25]
	s_mov_b32 m0, s21
	v_readfirstlane_b32 s24, v1
	v_add_u32_e32 v0, 0x22000, v0
	global_load_lds_dwordx4 v[2:3], off
	v_lshl_add_u64 v[2:3], v[78:79], 0, s[84:85]
	s_mov_b32 m0, s24
	v_readfirstlane_b32 s17, v0
	global_load_lds_dwordx4 v[2:3], off
	v_lshl_add_u64 v[2:3], v[78:79], 0, s[78:79]
	s_mov_b32 m0, s17
	v_add_u32_e32 v87, 0, v96
	v_add_u32_e32 v88, 0, v95
	global_load_lds_dwordx4 v[2:3], off
	v_add_u32_e32 v64, v87, v94
	v_add_u32_e32 v82, v88, v94
	v_lshlrev_b32_e32 v91, 4, v4
	ds_read_b128 v[4:7], v64
	ds_read_b128 v[0:3], v64 offset:4096
	ds_read_b128 v[8:11], v82 offset:32768
	ds_read_b128 v[12:15], v82 offset:36864
	s_waitcnt lgkmcnt(0)
	v_mfma_f32_32x32x16_bf16 v[48:63], v[8:11], v[4:7], 0
	v_add_u32_e32 v83, v87, v93
	v_add_u32_e32 v84, v88, v93
	ds_read_b128 v[66:69], v83
	ds_read_b128 v[70:73], v83 offset:4096
	ds_read_b128 v[98:101], v84 offset:32768
	ds_read_b128 v[102:105], v84 offset:36864
	v_add_u32_e32 v85, v87, v91
	v_add_u32_e32 v86, v88, v91
	ds_read_b128 v[106:109], v85
	ds_read_b128 v[110:113], v85 offset:4096
	v_mfma_f32_32x32x16_bf16 v[32:47], v[12:15], v[4:7], 0
	ds_read_b128 v[114:117], v86 offset:32768
	ds_read_b128 v[118:121], v86 offset:36864
	v_add_u32_e32 v87, v87, v90
	v_add_u32_e32 v88, v88, v90
	s_mov_b32 m0, s16
	s_mov_b64 vcc, 0x30180
	s_add_i32 s25, 0, 0x14000
	v_add_u32_e32 v97, s25, v95
	v_mfma_f32_32x32x16_bf16 v[16:31], v[8:11], v[0:3], 0
	v_add_u32_e32 v89, v97, v94
	v_add_u32_e32 v92, v97, v93
	s_add_i32 s25, 0, 0x18000
	v_add_u32_e32 v128, s25, v96
	v_add_u32_e32 v129, s42, v95
	s_add_i32 s1, s1, s70
	s_cmp_ge_i32 s1, s54
	v_mfma_f32_32x32x16_bf16 v[0:15], v[12:15], v[0:3], 0
	s_waitcnt lgkmcnt(0)
	v_mfma_f32_32x32x16_bf16 v[48:63], v[98:101], v[66:69], v[48:63]
	v_mfma_f32_32x32x16_bf16 v[32:47], v[102:105], v[66:69], v[32:47]
	v_mfma_f32_32x32x16_bf16 v[16:31], v[98:101], v[70:73], v[16:31]
	v_mfma_f32_32x32x16_bf16 v[0:15], v[102:105], v[70:73], v[0:15]
	ds_read_b128 v[66:69], v87
	ds_read_b128 v[70:73], v87 offset:4096
	ds_read_b128 v[98:101], v88 offset:32768
	ds_read_b128 v[102:105], v88 offset:36864
	s_waitcnt vmcnt(6)
	s_barrier
; #define MFMA32(a, b, c) __builtin_amdgcn_mfma_f32_32x32x16_bf16((a), (b), (c), 0, 0, 0)
; template <int NI>
; DEVINL void gemm_kloop(const bf16_t* __restrict__ A, int lda, const bf16_t* __restrict__ Bt, int ldb, int K, int m0, int n0,
;                        unsigned char* lds, f32x16 (&acc)[NI][2]) {
;     ...
;         for (int ks = 0; ks < 4; ++ks) {
;             if (ks < 3) {
; #pragma unroll
;                 for (int i = 0; i < 2; ++i) af[(ks + 1) & 1][i] = *(const bf16x8*)(pa + i * 32 * 128 + o4[ks + 1]);
; #pragma unroll
;                 for (int i = 0; i < NI; ++i) bfr[(ks + 1) & 1][i] = *(const bf16x8*)(pb + i * 32 * 128 + o4[ks + 1]);
;             }
; #pragma unroll
;             for (int ni = 0; ni < NI; ++ni)
; #pragma unroll
;                 for (int mi = 0; mi < 2; ++mi) acc[ni][mi] = MFMA32(bfr[ks & 1][ni], af[ks & 1][mi], acc[ni][mi]);
;         }
;     };
;     int t = 0;
;     for (; t + 2 < nt; ++t) {
;         if (NI == 2) asm volatile("s_waitcnt vmcnt(6)" ::: "memory"); else asm volatile("s_waitcnt vmcnt(5)" ::: "memory");
;         __builtin_amdgcn_s_barrier();
;         { const int s2 = (cur >= 1) ? cur - 1 : 2; GEMM_ISSUE(s2, t + 2); }
;         compute(cur);
;         cur = (cur == 2) ? 0 : cur + 1;
;     }
	v_mfma_f32_32x32x16_bf16 v[48:63], v[114:117], v[106:109], v[48:63]
	v_mfma_f32_32x32x16_bf16 v[32:47], v[118:121], v[106:109], v[32:47]
	v_mfma_f32_32x32x16_bf16 v[16:31], v[114:117], v[110:113], v[16:31]
	v_mfma_f32_32x32x16_bf16 v[0:15], v[118:121], v[110:113], v[0:15]
	s_waitcnt lgkmcnt(0)
	v_mfma_f32_32x32x16_bf16 v[48:63], v[98:101], v[66:69], v[48:63]
	v_mfma_f32_32x32x16_bf16 v[32:47], v[102:105], v[66:69], v[32:47]
	v_lshl_add_u64 v[66:67], v[76:77], 0, s[88:89]
	global_load_lds_dwordx4 v[66:67], off
	v_lshl_add_u64 v[66:67], v[76:77], 0, s[80:81]
	s_mov_b32 m0, s15
	s_nop 0
	global_load_lds_dwordx4 v[66:67], off
	v_lshl_add_u64 v[66:67], v[76:77], 0, s[56:57]
	s_mov_b32 m0, s14
	v_mfma_f32_32x32x16_bf16 v[16:31], v[98:101], v[70:73], v[16:31]
	global_load_lds_dwordx4 v[66:67], off
	v_lshl_add_u64 v[66:67], v[76:77], 0, vcc
	s_mov_b32 m0, s13
	s_mov_b64 vcc, 0x30200
	global_load_lds_dwordx4 v[66:67], off
	v_lshl_add_u64 v[66:67], v[78:79], 0, s[88:89]
	s_mov_b32 m0, s12
	v_mfma_f32_32x32x16_bf16 v[0:15], v[102:105], v[70:73], v[0:15]
	global_load_lds_dwordx4 v[66:67], off
	v_lshl_add_u64 v[66:67], v[78:79], 0, s[80:81]
	s_mov_b32 m0, s11
	s_nop 0
	global_load_lds_dwordx4 v[66:67], off
	ds_read_b128 v[70:73], v64 offset:49152
	ds_read_b128 v[66:69], v64 offset:53248
	ds_read_b128 v[98:101], v89
	ds_read_b128 v[102:105], v89 offset:4096
	ds_read_b128 v[106:109], v83 offset:49152
	ds_read_b128 v[110:113], v83 offset:53248
	s_waitcnt lgkmcnt(0)
	v_mfma_f32_32x32x16_bf16 v[48:63], v[98:101], v[70:73], v[48:63]
	ds_read_b128 v[114:117], v92
	ds_read_b128 v[118:121], v92 offset:4096
	s_mov_b32 m0, s10
	v_mfma_f32_32x32x16_bf16 v[32:47], v[102:105], v[70:73], v[32:47]
	v_mfma_f32_32x32x16_bf16 v[16:31], v[98:101], v[66:69], v[16:31]
	ds_read_b128 v[70:73], v85 offset:49152
	ds_read_b128 v[98:101], v85 offset:53248
	v_mfma_f32_32x32x16_bf16 v[0:15], v[102:105], v[66:69], v[0:15]
	v_add_u32_e32 v68, v97, v91
	ds_read_b128 v[102:105], v68
	ds_read_b128 v[122:125], v68 offset:4096
	v_add_u32_e32 v69, v97, v90
	v_lshl_add_u64 v[66:67], v[76:77], 0, s[58:59]
	s_waitcnt lgkmcnt(0)
	v_mfma_f32_32x32x16_bf16 v[48:63], v[114:117], v[106:109], v[48:63]
	v_mfma_f32_32x32x16_bf16 v[32:47], v[118:121], v[106:109], v[32:47]
	v_mfma_f32_32x32x16_bf16 v[16:31], v[114:117], v[110:113], v[16:31]
	v_mfma_f32_32x32x16_bf16 v[0:15], v[118:121], v[110:113], v[0:15]
	ds_read_b128 v[106:109], v87 offset:49152
	ds_read_b128 v[110:113], v87 offset:53248
	ds_read_b128 v[114:117], v69
	ds_read_b128 v[118:121], v69 offset:4096
	s_waitcnt vmcnt(6)
	s_barrier
	global_load_lds_dwordx4 v[66:67], off
	v_lshl_add_u64 v[66:67], v[76:77], 0, s[82:83]
	v_mfma_f32_32x32x16_bf16 v[48:63], v[102:105], v[70:73], v[48:63]
	s_mov_b32 m0, s9
	s_nop 0
	global_load_lds_dwordx4 v[66:67], off
	v_lshl_add_u64 v[66:67], v[76:77], 0, s[96:97]
	s_mov_b32 m0, s8
	v_mfma_f32_32x32x16_bf16 v[32:47], v[122:125], v[70:73], v[32:47]
	global_load_lds_dwordx4 v[66:67], off
	v_lshl_add_u64 v[66:67], v[76:77], 0, vcc
	s_mov_b32 m0, s7
	v_add_u32_e32 v70, v128, v93
	global_load_lds_dwordx4 v[66:67], off
	v_mfma_f32_32x32x16_bf16 v[16:31], v[102:105], v[98:101], v[16:31]
	v_lshl_add_u64 v[66:67], v[78:79], 0, s[58:59]
	s_mov_b32 m0, s6
	v_add_u32_e32 v71, v129, v93
	global_load_lds_dwordx4 v[66:67], off
	v_lshl_add_u64 v[66:67], v[78:79], 0, s[82:83]
	s_mov_b32 m0, s5
	v_mfma_f32_32x32x16_bf16 v[0:15], v[122:125], v[98:101], v[0:15]
	global_load_lds_dwordx4 v[66:67], off
	v_add_u32_e32 v66, v128, v94
	v_add_u32_e32 v67, v129, v94
	ds_read_b128 v[96:99], v66
	ds_read_b128 v[100:103], v66 offset:4096
	v_add_u32_e32 v72, v128, v91
	v_add_u32_e32 v73, v129, v91
	s_waitcnt lgkmcnt(0)
	v_mfma_f32_32x32x16_bf16 v[48:63], v[114:117], v[106:109], v[48:63]
	v_add_u32_e32 v91, v128, v90
	v_add_u32_e32 v90, v129, v90
	s_mov_b32 m0, s19
	v_mfma_f32_32x32x16_bf16 v[32:47], v[118:121], v[106:109], v[32:47]
	v_mfma_f32_32x32x16_bf16 v[16:31], v[114:117], v[110:113], v[16:31]
	v_mfma_f32_32x32x16_bf16 v[0:15], v[118:121], v[110:113], v[0:15]
	ds_read_b128 v[104:107], v67
	ds_read_b128 v[108:111], v67 offset:4096
	ds_read_b128 v[112:115], v70
	ds_read_b128 v[116:119], v70 offset:4096
	ds_read_b128 v[120:123], v71
	ds_read_b128 v[124:127], v71 offset:4096
	s_waitcnt lgkmcnt(0)
	v_mfma_f32_32x32x16_bf16 v[48:63], v[104:107], v[96:99], v[48:63]
	v_mfma_f32_32x32x16_bf16 v[32:47], v[108:111], v[96:99], v[32:47]
	v_mfma_f32_32x32x16_bf16 v[16:31], v[104:107], v[100:103], v[16:31]
	v_mfma_f32_32x32x16_bf16 v[0:15], v[108:111], v[100:103], v[0:15]
	ds_read_b128 v[94:97], v72
	ds_read_b128 v[98:101], v72 offset:4096
	ds_read_b128 v[102:105], v73
	ds_read_b128 v[106:109], v73 offset:4096
	v_mfma_f32_32x32x16_bf16 v[48:63], v[120:123], v[112:115], v[48:63]
	v_mfma_f32_32x32x16_bf16 v[32:47], v[124:127], v[112:115], v[32:47]
	v_mfma_f32_32x32x16_bf16 v[16:31], v[120:123], v[116:119], v[16:31]
	v_mfma_f32_32x32x16_bf16 v[0:15], v[124:127], v[116:119], v[0:15]
	ds_read_b128 v[110:113], v91
	ds_read_b128 v[114:117], v91 offset:4096
	ds_read_b128 v[118:121], v90
	ds_read_b128 v[122:125], v90 offset:4096
	s_waitcnt vmcnt(6)
	s_barrier
; #define MFMA32(a, b, c) __builtin_amdgcn_mfma_f32_32x32x16_bf16((a), (b), (c), 0, 0, 0)
; template <int NI>
; DEVINL void gemm_kloop(const bf16_t* __restrict__ A, int lda, const bf16_t* __restrict__ Bt, int ldb, int K, int m0, int n0,
;                        unsigned char* lds, f32x16 (&acc)[NI][2]) {
;     ...
;         for (int ks = 0; ks < 4; ++ks) {
;             if (ks < 3) {
; #pragma unroll
;                 for (int i = 0; i < 2; ++i) af[(ks + 1) & 1][i] = *(const bf16x8*)(pa + i * 32 * 128 + o4[ks + 1]);
; #pragma unroll
;                 for (int i = 0; i < NI; ++i) bfr[(ks + 1) & 1][i] = *(const bf16x8*)(pb + i * 32 * 128 + o4[ks + 1]);
;             }
; #pragma unroll
;             for (int ni = 0; ni < NI; ++ni)
; #pragma unroll
;                 for (int mi = 0; mi < 2; ++mi) acc[ni][mi] = MFMA32(bfr[ks & 1][ni], af[ks & 1][mi], acc[ni][mi]);
;         }
;     };
;     int t = 0;
;     for (; t + 2 < nt; ++t) {
;         if (NI == 2) asm volatile("s_waitcnt vmcnt(6)" ::: "memory"); else asm volatile("s_waitcnt vmcnt(5)" ::: "memory");
;         __builtin_amdgcn_s_barrier();
;         { const int s2 = (cur >= 1) ? cur - 1 : 2; GEMM_ISSUE(s2, t + 2); }
;         compute(cur);
;         cur = (cur == 2) ? 0 : cur + 1;
;     }
	s_waitcnt lgkmcnt(0)
	v_mfma_f32_32x32x16_bf16 v[48:63], v[102:105], v[94:97], v[48:63]
	v_mfma_f32_32x32x16_bf16 v[32:47], v[106:109], v[94:97], v[32:47]
	v_lshl_add_u64 v[94:95], v[76:77], 0, s[64:65]
	global_load_lds_dwordx4 v[94:95], off
	v_lshl_add_u64 v[94:95], v[76:77], 0, s[22:23]
	s_mov_b32 m0, s18
	s_mov_b64 s[18:19], 0x30280
	global_load_lds_dwordx4 v[94:95], off
	v_mfma_f32_32x32x16_bf16 v[16:31], v[102:105], v[98:101], v[16:31]
	v_lshl_add_u64 v[94:95], v[76:77], 0, s[62:63]
	s_mov_b32 m0, s20
	s_nop 0
	global_load_lds_dwordx4 v[94:95], off
	v_lshl_add_u64 v[94:95], v[76:77], 0, s[18:19]
	s_mov_b32 m0, s21
	v_mfma_f32_32x32x16_bf16 v[0:15], v[106:109], v[98:101], v[0:15]
	global_load_lds_dwordx4 v[94:95], off
	v_lshl_add_u64 v[94:95], v[78:79], 0, s[64:65]
	s_mov_b32 m0, s24
	s_nop 0
	global_load_lds_dwordx4 v[94:95], off
	v_mfma_f32_32x32x16_bf16 v[48:63], v[118:121], v[110:113], v[48:63]
	v_lshl_add_u64 v[94:95], v[78:79], 0, s[22:23]
	s_mov_b32 m0, s17
	s_nop 0
	global_load_lds_dwordx4 v[94:95], off
	s_mov_b32 m0, s16
	v_mfma_f32_32x32x16_bf16 v[32:47], v[122:125], v[110:113], v[32:47]
	v_mfma_f32_32x32x16_bf16 v[16:31], v[118:121], v[114:117], v[16:31]
	v_mfma_f32_32x32x16_bf16 v[0:15], v[122:125], v[114:117], v[0:15]
	ds_read_b128 v[94:97], v64
	ds_read_b128 v[98:101], v64 offset:4096
	ds_read_b128 v[102:105], v82 offset:32768
	ds_read_b128 v[106:109], v82 offset:36864
	ds_read_b128 v[110:113], v83
	ds_read_b128 v[114:117], v83 offset:4096
	ds_read_b128 v[118:121], v84 offset:32768
	ds_read_b128 v[122:125], v84 offset:36864
	s_waitcnt lgkmcnt(0)
	v_mfma_f32_32x32x16_bf16 v[48:63], v[102:105], v[94:97], v[48:63]
	v_mfma_f32_32x32x16_bf16 v[32:47], v[106:109], v[94:97], v[32:47]
	v_mfma_f32_32x32x16_bf16 v[16:31], v[102:105], v[98:101], v[16:31]
	v_mfma_f32_32x32x16_bf16 v[0:15], v[106:109], v[98:101], v[0:15]
	ds_read_b128 v[94:97], v85
	ds_read_b128 v[98:101], v85 offset:4096
	ds_read_b128 v[102:105], v86 offset:32768
	ds_read_b128 v[106:109], v86 offset:36864
	v_mfma_f32_32x32x16_bf16 v[48:63], v[118:121], v[110:113], v[48:63]
	v_mfma_f32_32x32x16_bf16 v[32:47], v[122:125], v[110:113], v[32:47]
	v_mfma_f32_32x32x16_bf16 v[16:31], v[118:121], v[114:117], v[16:31]
	v_mfma_f32_32x32x16_bf16 v[0:15], v[122:125], v[114:117], v[0:15]
	ds_read_b128 v[110:113], v87
	ds_read_b128 v[114:117], v87 offset:4096
	ds_read_b128 v[118:121], v88 offset:32768
	ds_read_b128 v[122:125], v88 offset:36864
	s_waitcnt vmcnt(6)
	s_barrier
	s_waitcnt lgkmcnt(0)
	v_mfma_f32_32x32x16_bf16 v[48:63], v[102:105], v[94:97], v[48:63]
	v_mfma_f32_32x32x16_bf16 v[32:47], v[106:109], v[94:97], v[32:47]
	v_lshl_add_u64 v[94:95], v[76:77], 0, s[2:3]
	global_load_lds_dwordx4 v[94:95], off
	v_lshl_add_u64 v[94:95], v[76:77], 0, s[26:27]
	s_mov_b32 m0, s15
	s_nop 0
	global_load_lds_dwordx4 v[94:95], off
	v_mfma_f32_32x32x16_bf16 v[16:31], v[102:105], v[98:101], v[16:31]
	v_lshl_add_u64 v[94:95], v[76:77], 0, s[90:91]
	s_mov_b32 m0, s14
	s_mov_b64 s[14:15], 0x30300
	global_load_lds_dwordx4 v[94:95], off
	v_lshl_add_u64 v[94:95], v[76:77], 0, s[14:15]
	s_mov_b32 m0, s13
	v_mfma_f32_32x32x16_bf16 v[0:15], v[106:109], v[98:101], v[0:15]
	global_load_lds_dwordx4 v[94:95], off
	v_lshl_add_u64 v[94:95], v[78:79], 0, s[2:3]
	s_mov_b32 m0, s12
	s_nop 0
	global_load_lds_dwordx4 v[94:95], off
	v_mfma_f32_32x32x16_bf16 v[48:63], v[118:121], v[110:113], v[48:63]
	v_lshl_add_u64 v[94:95], v[78:79], 0, s[26:27]
	s_mov_b32 m0, s11
	s_nop 0
	global_load_lds_dwordx4 v[94:95], off
	s_mov_b32 m0, s10
	v_mfma_f32_32x32x16_bf16 v[32:47], v[122:125], v[110:113], v[32:47]
	v_mfma_f32_32x32x16_bf16 v[16:31], v[118:121], v[114:117], v[16:31]
	v_mfma_f32_32x32x16_bf16 v[0:15], v[122:125], v[114:117], v[0:15]
	ds_read_b128 v[94:97], v64 offset:49152
	ds_read_b128 v[98:101], v64 offset:53248
	ds_read_b128 v[102:105], v89
	ds_read_b128 v[106:109], v89 offset:4096
	ds_read_b128 v[110:113], v83 offset:49152
	ds_read_b128 v[114:117], v83 offset:53248
	ds_read_b128 v[118:121], v92
	ds_read_b128 v[122:125], v92 offset:4096
	s_waitcnt lgkmcnt(0)
	v_mfma_f32_32x32x16_bf16 v[48:63], v[102:105], v[94:97], v[48:63]
	v_mfma_f32_32x32x16_bf16 v[32:47], v[106:109], v[94:97], v[32:47]
	v_mfma_f32_32x32x16_bf16 v[16:31], v[102:105], v[98:101], v[16:31]
	v_mfma_f32_32x32x16_bf16 v[0:15], v[106:109], v[98:101], v[0:15]
	ds_read_b128 v[94:97], v85 offset:49152
	ds_read_b128 v[98:101], v85 offset:53248
	ds_read_b128 v[102:105], v68
	ds_read_b128 v[106:109], v68 offset:4096
	v_mfma_f32_32x32x16_bf16 v[48:63], v[118:121], v[110:113], v[48:63]
	v_mfma_f32_32x32x16_bf16 v[32:47], v[122:125], v[110:113], v[32:47]
	v_mfma_f32_32x32x16_bf16 v[16:31], v[118:121], v[114:117], v[16:31]
	v_mfma_f32_32x32x16_bf16 v[0:15], v[122:125], v[114:117], v[0:15]
	ds_read_b128 v[110:113], v87 offset:49152
	ds_read_b128 v[114:117], v87 offset:53248
	ds_read_b128 v[118:121], v69
	ds_read_b128 v[122:125], v69 offset:4096
	s_waitcnt vmcnt(6)
	s_barrier
;     DEVINL bf16_t* Z() const { return (bf16_t*)(ws + OFF_Z); }
; template <int NI>
; DEVINL void gemm_kloop(const bf16_t* __restrict__ A, int lda, const bf16_t* __restrict__ Bt, int ldb, int K, int m0, int n0,
;                        unsigned char* lds, f32x16 (&acc)[NI][2]) {
;     ...
;     for (; t + 2 < nt; ++t) {
;         if (NI == 2) asm volatile("s_waitcnt vmcnt(6)" ::: "memory"); else asm volatile("s_waitcnt vmcnt(5)" ::: "memory");
;         __builtin_amdgcn_s_barrier();
;         { const int s2 = (cur >= 1) ? cur - 1 : 2; GEMM_ISSUE(s2, t + 2); }
;         compute(cur);
;         cur = (cur == 2) ? 0 : cur + 1;
;     }
;     if (nt >= 2) {
;         if (NI == 2) asm volatile("s_waitcnt vmcnt(6)" ::: "memory"); else asm volatile("s_waitcnt vmcnt(5)" ::: "memory");
;         __builtin_amdgcn_s_barrier();
;         compute(cur);
;         cur = (cur == 2) ? 0 : cur + 1;
;     }
;     asm volatile("s_waitcnt vmcnt(0)" ::: "memory");
;     __builtin_amdgcn_s_barrier();
;     compute(cur);
; template <int NI, int MODE>
; DEVINL void merge_tile(const Ctx& c, unsigned char* lds, int m0, int n0) {
;     ...
; #pragma unroll
;         for (int mi = 0; mi < 2; ++mi) {
;             const bf16_t* gp = c.Z() + (size_t)(mbase + mi * 32 + r) * ZW + Z_GZ + br * DM + nbase;
	s_waitcnt lgkmcnt(0)
	v_mfma_f32_32x32x16_bf16 v[48:63], v[102:105], v[94:97], v[48:63]
	v_mfma_f32_32x32x16_bf16 v[32:47], v[106:109], v[94:97], v[32:47]
	v_lshl_add_u64 v[94:95], v[76:77], 0, s[40:41]
	global_load_lds_dwordx4 v[94:95], off
	v_lshl_add_u64 v[94:95], v[76:77], 0, s[44:45]
	s_mov_b32 m0, s9
	s_nop 0
	global_load_lds_dwordx4 v[94:95], off
	v_mfma_f32_32x32x16_bf16 v[16:31], v[102:105], v[98:101], v[16:31]
	v_lshl_add_u64 v[94:95], v[76:77], 0, s[72:73]
	s_mov_b32 m0, s8
	v_lshl_add_u64 v[76:77], v[76:77], 0, s[94:95]
	global_load_lds_dwordx4 v[94:95], off
	s_mov_b32 m0, s7
	v_mfma_f32_32x32x16_bf16 v[0:15], v[106:109], v[98:101], v[0:15]
	global_load_lds_dwordx4 v[76:77], off
	v_lshl_add_u64 v[76:77], v[78:79], 0, s[40:41]
	s_mov_b32 m0, s6
	s_nop 0
	global_load_lds_dwordx4 v[76:77], off
	v_mfma_f32_32x32x16_bf16 v[48:63], v[118:121], v[110:113], v[48:63]
	v_lshl_add_u64 v[76:77], v[78:79], 0, s[44:45]
	s_mov_b32 m0, s5
	s_nop 0
	global_load_lds_dwordx4 v[76:77], off
	v_mfma_f32_32x32x16_bf16 v[32:47], v[122:125], v[110:113], v[32:47]
	v_mfma_f32_32x32x16_bf16 v[16:31], v[118:121], v[114:117], v[16:31]
	v_mfma_f32_32x32x16_bf16 v[0:15], v[122:125], v[114:117], v[0:15]
	ds_read_b128 v[76:79], v66
	ds_read_b128 v[94:97], v66 offset:4096
	ds_read_b128 v[98:101], v67
	ds_read_b128 v[102:105], v67 offset:4096
	ds_read_b128 v[106:109], v70
	ds_read_b128 v[110:113], v70 offset:4096
	ds_read_b128 v[114:117], v71
	ds_read_b128 v[118:121], v71 offset:4096
	v_add_u32_e32 v66, s4, v81
	v_ashrrev_i32_e32 v67, 31, v66
	s_waitcnt lgkmcnt(0)
	v_mfma_f32_32x32x16_bf16 v[48:63], v[98:101], v[76:79], v[48:63]
	v_mfma_f32_32x32x16_bf16 v[32:47], v[102:105], v[76:79], v[32:47]
	v_mfma_f32_32x32x16_bf16 v[16:31], v[98:101], v[94:97], v[16:31]
	v_mfma_f32_32x32x16_bf16 v[0:15], v[102:105], v[94:97], v[0:15]
	ds_read_b128 v[76:79], v72
	ds_read_b128 v[94:97], v72 offset:4096
	ds_read_b128 v[98:101], v73
	ds_read_b128 v[70:73], v73 offset:4096
	v_mfma_f32_32x32x16_bf16 v[48:63], v[114:117], v[106:109], v[48:63]
	v_mfma_f32_32x32x16_bf16 v[32:47], v[118:121], v[106:109], v[32:47]
	v_mfma_f32_32x32x16_bf16 v[16:31], v[114:117], v[110:113], v[16:31]
	v_mfma_f32_32x32x16_bf16 v[0:15], v[118:121], v[110:113], v[0:15]
	ds_read_b128 v[102:105], v91
	ds_read_b128 v[106:109], v91 offset:4096
	ds_read_b128 v[110:113], v90
	ds_read_b128 v[114:117], v90 offset:4096
	s_waitcnt vmcnt(6)
	s_barrier
	s_waitcnt lgkmcnt(0)
	v_mfma_f32_32x32x16_bf16 v[48:63], v[98:101], v[76:79], v[48:63]
	v_mfma_f32_32x32x16_bf16 v[32:47], v[70:73], v[76:79], v[32:47]
	v_mfma_f32_32x32x16_bf16 v[16:31], v[98:101], v[94:97], v[16:31]
	v_mfma_f32_32x32x16_bf16 v[0:15], v[70:73], v[94:97], v[0:15]
	v_mfma_f32_32x32x16_bf16 v[48:63], v[110:113], v[102:105], v[48:63]
	v_mfma_f32_32x32x16_bf16 v[32:47], v[114:117], v[102:105], v[32:47]
	v_mfma_f32_32x32x16_bf16 v[16:31], v[110:113], v[106:109], v[16:31]
	v_mfma_f32_32x32x16_bf16 v[0:15], v[114:117], v[106:109], v[0:15]
	ds_read_b128 v[70:73], v64
	ds_read_b128 v[76:79], v64 offset:4096
	ds_read_b128 v[94:97], v82 offset:32768
	ds_read_b128 v[98:101], v82 offset:36864
	ds_read_b128 v[102:105], v83
	ds_read_b128 v[106:109], v83 offset:4096
	ds_read_b128 v[110:113], v84 offset:32768
	ds_read_b128 v[114:117], v84 offset:36864
	s_waitcnt lgkmcnt(0)
	v_mfma_f32_32x32x16_bf16 v[48:63], v[94:97], v[70:73], v[48:63]
	v_mfma_f32_32x32x16_bf16 v[32:47], v[98:101], v[70:73], v[32:47]
	v_mfma_f32_32x32x16_bf16 v[16:31], v[94:97], v[76:79], v[16:31]
	v_mfma_f32_32x32x16_bf16 v[0:15], v[98:101], v[76:79], v[0:15]
	ds_read_b128 v[70:73], v85
	ds_read_b128 v[76:79], v85 offset:4096
	ds_read_b128 v[94:97], v86 offset:32768
	ds_read_b128 v[98:101], v86 offset:36864
	v_mfma_f32_32x32x16_bf16 v[48:63], v[110:113], v[102:105], v[48:63]
	v_mfma_f32_32x32x16_bf16 v[32:47], v[114:117], v[102:105], v[32:47]
	v_mfma_f32_32x32x16_bf16 v[16:31], v[110:113], v[106:109], v[16:31]
	v_mfma_f32_32x32x16_bf16 v[0:15], v[114:117], v[106:109], v[0:15]
	ds_read_b128 v[102:105], v87
	ds_read_b128 v[106:109], v87 offset:4096
	ds_read_b128 v[110:113], v88 offset:32768
	ds_read_b128 v[114:117], v88 offset:36864
	s_waitcnt vmcnt(0)
	s_barrier
	s_waitcnt lgkmcnt(0)
	v_mfma_f32_32x32x16_bf16 v[48:63], v[94:97], v[70:73], v[48:63]
	v_mfma_f32_32x32x16_bf16 v[32:47], v[98:101], v[70:73], v[32:47]
	v_mfma_f32_32x32x16_bf16 v[16:31], v[94:97], v[76:79], v[16:31]
	v_mfma_f32_32x32x16_bf16 v[0:15], v[98:101], v[76:79], v[0:15]
	v_mfma_f32_32x32x16_bf16 v[48:63], v[110:113], v[102:105], v[48:63]
	v_mfma_f32_32x32x16_bf16 v[32:47], v[114:117], v[102:105], v[32:47]
	v_mfma_f32_32x32x16_bf16 v[16:31], v[110:113], v[106:109], v[16:31]
	v_mfma_f32_32x32x16_bf16 v[0:15], v[114:117], v[106:109], v[0:15]
	ds_read_b128 v[70:73], v64 offset:49152
	ds_read_b128 v[76:79], v64 offset:53248
	ds_read_b128 v[94:97], v89
	ds_read_b128 v[88:91], v89 offset:4096
	ds_read_b128 v[98:101], v83 offset:49152
	ds_read_b128 v[102:105], v83 offset:53248
	ds_read_b128 v[106:109], v92
	ds_read_b128 v[110:113], v92 offset:4096
	v_lshlrev_b32_e32 v64, 1, v80
	s_waitcnt lgkmcnt(0)
	v_mfma_f32_32x32x16_bf16 v[48:63], v[94:97], v[70:73], v[48:63]
	v_mfma_f32_32x32x16_bf16 v[32:47], v[88:91], v[70:73], v[32:47]
	v_mfma_f32_32x32x16_bf16 v[16:31], v[94:97], v[76:79], v[16:31]
	v_mfma_f32_32x32x16_bf16 v[0:15], v[88:91], v[76:79], v[0:15]
	ds_read_b128 v[70:73], v85 offset:49152
	ds_read_b128 v[76:79], v85 offset:53248
	ds_read_b128 v[82:85], v68
	ds_read_b128 v[88:91], v68 offset:4096
	v_mfma_f32_32x32x16_bf16 v[48:63], v[106:109], v[98:101], v[48:63]
	v_mfma_f32_32x32x16_bf16 v[32:47], v[110:113], v[98:101], v[32:47]
	v_mfma_f32_32x32x16_bf16 v[16:31], v[106:109], v[102:105], v[16:31]
	v_mfma_f32_32x32x16_bf16 v[0:15], v[110:113], v[102:105], v[0:15]
	ds_read_b128 v[92:95], v87 offset:49152
	ds_read_b128 v[96:99], v87 offset:53248
	ds_read_b128 v[100:103], v69
	ds_read_b128 v[104:107], v69 offset:4096
	v_mov_b64_e32 v[68:69], s[28:29]
	v_or_b32_e32 v112, 32, v75
	s_waitcnt lgkmcnt(0)
;     DEVINL bf16_t* Z() const { return (bf16_t*)(ws + OFF_Z); }
; DEVINL float bflo(unsigned u) { return __uint_as_float(u << 16); }
; DEVINL float bfhi(unsigned u) { return __uint_as_float(u & 0xffff0000u); }
; DEVINL float* mp_row(const Ctx& c, int t) { return (float*)(c.Z() + (size_t)t * ZW); }
; template <int NI, int MODE>
; DEVINL void merge_tile(const Ctx& c, unsigned char* lds, int m0, int n0) {
;     ...
; #pragma unroll
;         for (int mi = 0; mi < 2; ++mi) {
;             const bf16_t* gp = c.Z() + (size_t)(mbase + mi * 32 + r) * ZW + Z_GZ + br * DM + nbase;
; #pragma unroll
;             for (int ni = 0; ni < NI; ++ni)
; #pragma unroll
;                 for (int g = 0; g < 4; ++g) {
;                     const u32x2 gg = *(const u32x2*)(gp + ni * 32 + 8 * g + 4 * h);
;                     mer[ni][mi][4 * g + 0] += bflo(gg[0]) * acc[ni][mi][4 * g + 0];
;                     mer[ni][mi][4 * g + 1] += bfhi(gg[0]) * acc[ni][mi][4 * g + 1];
;                     mer[ni][mi][4 * g + 2] += bflo(gg[1]) * acc[ni][mi][4 * g + 2];
;                     mer[ni][mi][4 * g + 3] += bfhi(gg[1]) * acc[ni][mi][4 * g + 3];
;                 }
;     ...
; #pragma unroll
;     for (int mi = 0; mi < 2; ++mi) {
;         const float* pp = mp_row(c, mbase + mi * 32 + r) + nbase;
; #pragma unroll
;         for (int ni = 0; ni < NI; ++ni)
; #pragma unroll
;             for (int g = 0; g < 4; ++g) {
;                 const f32x4 v = *(const f32x4*)(pp + ni * 32 + 8 * g + 4 * h);
; #pragma unroll
;                 for (int j = 0; j < 4; ++j) mer[ni][mi][4 * g + j] += v[j];
;             }
;     }
	v_mfma_f32_32x32x16_bf16 v[48:63], v[82:85], v[70:73], v[48:63]
	v_mfma_f32_32x32x16_bf16 v[32:47], v[88:91], v[70:73], v[32:47]
	v_mad_i64_i32 v[70:71], s[4:5], v75, s49, v[68:69]
	v_lshlrev_b64 v[72:73], 1, v[66:67]
	v_lshl_add_u64 v[70:71], v[70:71], 0, v[72:73]
	v_lshl_add_u64 v[70:71], v[70:71], 0, v[64:65]
	v_mad_i64_i32 v[68:69], s[4:5], v112, s49, v[68:69]
	v_mfma_f32_32x32x16_bf16 v[16:31], v[82:85], v[76:79], v[16:31]
	v_lshl_add_u64 v[68:69], v[68:69], 0, v[72:73]
	v_lshl_add_u64 v[68:69], v[68:69], 0, v[64:65]
	v_lshl_add_u64 v[66:67], v[66:67], 2, s[30:31]
	v_lshlrev_b32_e32 v64, 2, v80
	v_lshl_add_u64 v[80:81], v[66:67], 0, v[64:65]
	v_mad_i64_i32 v[108:109], s[4:5], v75, s49, v[80:81]
	v_mad_i64_i32 v[232:233], s[4:5], v112, s49, v[80:81]
	global_load_dwordx4 v[168:171], v[108:109], off
	global_load_dwordx4 v[172:175], v[108:109], off offset:32
	global_load_dwordx4 v[176:179], v[108:109], off offset:64
	global_load_dwordx4 v[180:183], v[108:109], off offset:96
	global_load_dwordx4 v[184:187], v[108:109], off offset:128
	global_load_dwordx4 v[188:191], v[108:109], off offset:160
	global_load_dwordx4 v[192:195], v[108:109], off offset:192
	global_load_dwordx4 v[196:199], v[108:109], off offset:224
	global_load_dwordx4 v[200:203], v[232:233], off
	global_load_dwordx4 v[204:207], v[232:233], off offset:32
	global_load_dwordx4 v[208:211], v[232:233], off offset:64
	global_load_dwordx4 v[212:215], v[232:233], off offset:96
	global_load_dwordx4 v[216:219], v[232:233], off offset:128
	global_load_dwordx4 v[220:223], v[232:233], off offset:160
	global_load_dwordx4 v[224:227], v[232:233], off offset:192
	global_load_dwordx4 v[228:231], v[232:233], off offset:224
	v_mfma_f32_32x32x16_bf16 v[0:15], v[88:91], v[76:79], v[0:15]
	v_lshl_add_u64 v[76:77], v[70:71], 0, s[50:51]
	v_add_co_u32_e32 v70, vcc, s38, v70
	v_ashrrev_i32_e32 v75, 31, v74
	s_nop 0
	v_addc_co_u32_e32 v71, vcc, 0, v71, vcc
	global_load_dwordx2 v[70:71], v[70:71], off offset:768
	s_nop 0
	global_load_dwordx2 v[78:79], v[76:77], off offset:16
	global_load_dwordx2 v[82:83], v[76:77], off offset:32
	global_load_dwordx2 v[84:85], v[76:77], off offset:48
	global_load_dwordx2 v[86:87], v[76:77], off offset:64
	global_load_dwordx2 v[88:89], v[76:77], off offset:80
	global_load_dwordx2 v[90:91], v[76:77], off offset:96
	s_nop 0
	global_load_dwordx2 v[76:77], v[76:77], off offset:112
	v_mfma_f32_32x32x16_bf16 v[48:63], v[100:103], v[92:95], v[48:63]
	s_waitcnt vmcnt(0)
	v_lshlrev_b32_e32 v110, 16, v70
	v_mfma_f32_32x32x16_bf16 v[32:47], v[104:107], v[92:95], v[32:47]
	v_lshl_add_u64 v[92:93], v[68:69], 0, s[50:51]
	v_add_co_u32_e32 v68, vcc, s38, v68
	v_and_b32_e32 v111, 0xffff0000, v70
	s_nop 0
	v_addc_co_u32_e32 v69, vcc, 0, v69, vcc
	s_nop 3
	v_fma_f32 v48, v48, v110, 0
	v_fma_f32 v49, v49, v111, 0
	v_mfma_f32_32x32x16_bf16 v[16:31], v[100:103], v[96:99], v[16:31]
	v_lshlrev_b32_e32 v70, 16, v78
	v_mfma_f32_32x32x16_bf16 v[0:15], v[104:107], v[96:99], v[0:15]
	global_load_dwordx2 v[94:95], v[68:69], off offset:768
	global_load_dwordx2 v[96:97], v[92:93], off offset:16
	global_load_dwordx2 v[98:99], v[92:93], off offset:32
	global_load_dwordx2 v[100:101], v[92:93], off offset:48
	global_load_dwordx2 v[102:103], v[92:93], off offset:64
	global_load_dwordx2 v[104:105], v[92:93], off offset:80
	global_load_dwordx2 v[106:107], v[92:93], off offset:96
	s_nop 0
	global_load_dwordx2 v[92:93], v[92:93], off offset:112
	s_nop 0
	v_mov_b64_e32 v[66:67], v[168:169]
	v_mov_b64_e32 v[68:69], v[170:171]
	s_waitcnt vmcnt(0)
	v_pk_add_f32 v[66:67], v[48:49], v[66:67]
	v_lshlrev_b32_e32 v48, 16, v71
	v_and_b32_e32 v49, 0xffff0000, v71
	v_pk_fma_f32 v[48:49], v[50:51], v[48:49], 0 op_sel_hi:[1,1,0]
	v_and_b32_e32 v71, 0xffff0000, v78
	v_pk_add_f32 v[68:69], v[48:49], v[68:69]
	v_mov_b64_e32 v[48:49], v[172:173]
	v_mov_b64_e32 v[50:51], v[174:175]
	v_pk_fma_f32 v[52:53], v[52:53], v[70:71], 0 op_sel_hi:[1,1,0]
	v_lshlrev_b32_e32 v70, 16, v82
	v_and_b32_e32 v71, 0xffff0000, v82
	v_pk_fma_f32 v[56:57], v[56:57], v[70:71], 0 op_sel_hi:[1,1,0]
	v_lshlrev_b32_e32 v70, 16, v84
	v_and_b32_e32 v71, 0xffff0000, v84
	v_pk_fma_f32 v[60:61], v[60:61], v[70:71], 0 op_sel_hi:[1,1,0]
	v_lshlrev_b32_e32 v70, 16, v86
	v_and_b32_e32 v71, 0xffff0000, v86
	v_pk_fma_f32 v[32:33], v[32:33], v[70:71], 0 op_sel_hi:[1,1,0]
	v_lshlrev_b32_e32 v70, 16, v88
	v_and_b32_e32 v71, 0xffff0000, v88
	v_pk_fma_f32 v[36:37], v[36:37], v[70:71], 0 op_sel_hi:[1,1,0]
	v_lshlrev_b32_e32 v70, 16, v90
	v_and_b32_e32 v71, 0xffff0000, v90
	v_pk_fma_f32 v[40:41], v[40:41], v[70:71], 0 op_sel_hi:[1,1,0]
	v_lshlrev_b32_e32 v70, 16, v76
	v_and_b32_e32 v71, 0xffff0000, v76
	v_pk_fma_f32 v[44:45], v[44:45], v[70:71], 0 op_sel_hi:[1,1,0]
	v_mad_i64_i32 v[70:71], s[4:5], v112, s49, v[80:81]
	v_lshlrev_b32_e32 v76, 16, v94
	s_nop 0
	v_pk_add_f32 v[52:53], v[52:53], v[48:49]
	v_lshlrev_b32_e32 v48, 16, v79
	v_and_b32_e32 v49, 0xffff0000, v79
	v_pk_fma_f32 v[48:49], v[54:55], v[48:49], 0 op_sel_hi:[1,1,0]
	s_nop 0
	v_pk_add_f32 v[54:55], v[48:49], v[50:51]
	v_mov_b64_e32 v[48:49], v[176:177]
	v_mov_b64_e32 v[50:51], v[178:179]
	s_nop 0
	v_pk_add_f32 v[56:57], v[56:57], v[48:49]
	v_lshlrev_b32_e32 v48, 16, v83
	v_and_b32_e32 v49, 0xffff0000, v83
	v_pk_fma_f32 v[48:49], v[58:59], v[48:49], 0 op_sel_hi:[1,1,0]
	s_nop 0
	v_pk_add_f32 v[58:59], v[48:49], v[50:51]
	v_mov_b64_e32 v[48:49], v[180:181]
	v_mov_b64_e32 v[50:51], v[182:183]
	s_nop 0
	v_pk_add_f32 v[60:61], v[60:61], v[48:49]
	v_lshlrev_b32_e32 v48, 16, v85
	v_and_b32_e32 v49, 0xffff0000, v85
	v_pk_fma_f32 v[48:49], v[62:63], v[48:49], 0 op_sel_hi:[1,1,0]
	s_nop 0
	v_pk_add_f32 v[62:63], v[48:49], v[50:51]
; DEVINL unsigned cvt_pk_bf16(float lo, float hi) { const f32x2 v = {lo, hi}; return __builtin_bit_cast(unsigned, __builtin_convertvector(v, bf16x2v)); }
; DEVINL float* mp_row(const Ctx& c, int t) { return (float*)(c.Z() + (size_t)t * ZW); }
; template <int NI, int MODE>
; DEVINL void merge_tile(const Ctx& c, unsigned char* lds, int m0, int n0) {
;     ...
; #pragma unroll
;     for (int mi = 0; mi < 2; ++mi) {
;         const float* pp = mp_row(c, mbase + mi * 32 + r) + nbase;
; #pragma unroll
;         for (int ni = 0; ni < NI; ++ni)
; #pragma unroll
;             for (int g = 0; g < 4; ++g) {
;                 const f32x4 v = *(const f32x4*)(pp + ni * 32 + 8 * g + 4 * h);
; #pragma unroll
;                 for (int j = 0; j < 4; ++j) mer[ni][mi][4 * g + j] += v[j];
;             }
;     }
;     if (NI == 2) {
;         u32x2 pkm[2][2][4];
; #pragma unroll
;         for (int mi = 0; mi < 2; ++mi)
; #pragma unroll
;             for (int ni = 0; ni < 2; ++ni)
; #pragma unroll
;                 for (int g = 0; g < 4; ++g) { pkm[mi][ni][g][0] = cvt_pk_bf16(mer[ni % NI][mi][4 * g], mer[ni % NI][mi][4 * g + 1]); pkm[mi][ni][g][1] = cvt_pk_bf16(mer[ni % NI][mi][4 * g + 2], mer[ni % NI][mi][4 * g + 3]); }
	v_mov_b64_e32 v[48:49], v[184:185]
	v_mov_b64_e32 v[50:51], v[186:187]
	s_nop 0
	v_pk_add_f32 v[48:49], v[32:33], v[48:49]
	v_lshlrev_b32_e32 v32, 16, v87
	v_and_b32_e32 v33, 0xffff0000, v87
	v_pk_fma_f32 v[32:33], v[34:35], v[32:33], 0 op_sel_hi:[1,1,0]
	s_nop 0
	v_pk_add_f32 v[50:51], v[32:33], v[50:51]
	v_mov_b64_e32 v[32:33], v[188:189]
	v_mov_b64_e32 v[34:35], v[190:191]
	s_nop 0
	v_pk_add_f32 v[36:37], v[36:37], v[32:33]
	v_lshlrev_b32_e32 v32, 16, v89
	v_and_b32_e32 v33, 0xffff0000, v89
	v_pk_fma_f32 v[32:33], v[38:39], v[32:33], 0 op_sel_hi:[1,1,0]
	s_nop 0
	v_pk_add_f32 v[38:39], v[32:33], v[34:35]
	v_mov_b64_e32 v[32:33], v[192:193]
	v_mov_b64_e32 v[34:35], v[194:195]
	s_nop 0
	v_pk_add_f32 v[40:41], v[40:41], v[32:33]
	v_lshlrev_b32_e32 v32, 16, v91
	v_and_b32_e32 v33, 0xffff0000, v91
	v_pk_fma_f32 v[32:33], v[42:43], v[32:33], 0 op_sel_hi:[1,1,0]
	s_nop 0
	v_pk_add_f32 v[42:43], v[32:33], v[34:35]
	v_mov_b64_e32 v[32:33], v[196:197]
	v_mov_b64_e32 v[34:35], v[198:199]
	s_nop 0
	v_pk_add_f32 v[44:45], v[44:45], v[32:33]
	v_lshlrev_b32_e32 v32, 16, v77
	v_and_b32_e32 v33, 0xffff0000, v77
	v_pk_fma_f32 v[32:33], v[46:47], v[32:33], 0 op_sel_hi:[1,1,0]
	v_and_b32_e32 v77, 0xffff0000, v94
	v_pk_add_f32 v[46:47], v[32:33], v[34:35]
	v_mov_b64_e32 v[32:33], v[200:201]
	v_mov_b64_e32 v[34:35], v[202:203]
	v_pk_fma_f32 v[16:17], v[16:17], v[76:77], 0 op_sel_hi:[1,1,0]
	v_lshlrev_b32_e32 v76, 16, v96
	v_and_b32_e32 v77, 0xffff0000, v96
	v_pk_fma_f32 v[20:21], v[20:21], v[76:77], 0 op_sel_hi:[1,1,0]
	v_lshlrev_b32_e32 v76, 16, v98
	v_and_b32_e32 v77, 0xffff0000, v98
	v_pk_fma_f32 v[24:25], v[24:25], v[76:77], 0 op_sel_hi:[1,1,0]
	v_lshlrev_b32_e32 v76, 16, v100
	v_and_b32_e32 v77, 0xffff0000, v100
	v_pk_fma_f32 v[28:29], v[28:29], v[76:77], 0 op_sel_hi:[1,1,0]
	v_lshlrev_b32_e32 v76, 16, v102
	v_and_b32_e32 v77, 0xffff0000, v102
	v_pk_fma_f32 v[0:1], v[0:1], v[76:77], 0 op_sel_hi:[1,1,0]
	s_nop 0
	v_pk_add_f32 v[32:33], v[16:17], v[32:33]
	v_lshlrev_b32_e32 v16, 16, v95
	v_and_b32_e32 v17, 0xffff0000, v95
	v_pk_fma_f32 v[16:17], v[18:19], v[16:17], 0 op_sel_hi:[1,1,0]
	s_nop 0
	v_pk_add_f32 v[34:35], v[16:17], v[34:35]
	v_mov_b64_e32 v[16:17], v[204:205]
	v_mov_b64_e32 v[18:19], v[206:207]
	s_nop 0
	v_pk_add_f32 v[20:21], v[20:21], v[16:17]
	v_lshlrev_b32_e32 v16, 16, v97
	v_and_b32_e32 v17, 0xffff0000, v97
	v_pk_fma_f32 v[16:17], v[22:23], v[16:17], 0 op_sel_hi:[1,1,0]
	s_nop 0
	v_pk_add_f32 v[22:23], v[16:17], v[18:19]
	v_mov_b64_e32 v[16:17], v[208:209]
	v_mov_b64_e32 v[18:19], v[210:211]
	s_nop 0
	v_pk_add_f32 v[24:25], v[24:25], v[16:17]
	v_lshlrev_b32_e32 v16, 16, v99
	v_and_b32_e32 v17, 0xffff0000, v99
	v_pk_fma_f32 v[16:17], v[26:27], v[16:17], 0 op_sel_hi:[1,1,0]
	s_nop 0
	v_pk_add_f32 v[26:27], v[16:17], v[18:19]
	v_mov_b64_e32 v[16:17], v[212:213]
	v_mov_b64_e32 v[18:19], v[214:215]
	s_nop 0
	v_pk_add_f32 v[28:29], v[28:29], v[16:17]
	v_lshlrev_b32_e32 v16, 16, v101
	v_and_b32_e32 v17, 0xffff0000, v101
	v_pk_fma_f32 v[16:17], v[30:31], v[16:17], 0 op_sel_hi:[1,1,0]
	s_nop 0
	v_pk_add_f32 v[30:31], v[16:17], v[18:19]
	v_mov_b64_e32 v[16:17], v[216:217]
	v_mov_b64_e32 v[18:19], v[218:219]
	s_nop 0
	v_pk_add_f32 v[76:77], v[0:1], v[16:17]
	v_lshlrev_b32_e32 v0, 16, v103
	v_and_b32_e32 v1, 0xffff0000, v103
	v_pk_fma_f32 v[0:1], v[2:3], v[0:1], 0 op_sel_hi:[1,1,0]
	v_lshlrev_b32_e32 v16, 16, v104
	v_pk_add_f32 v[78:79], v[0:1], v[18:19]
	v_mov_b64_e32 v[0:1], v[220:221]
	v_mov_b64_e32 v[2:3], v[222:223]
	v_and_b32_e32 v17, 0xffff0000, v104
	v_pk_fma_f32 v[4:5], v[4:5], v[16:17], 0 op_sel_hi:[1,1,0]
	v_cvt_pk_bf16_f32 v16, v44, v45
	v_cvt_pk_bf16_f32 v17, v46, v47
	v_cvt_pk_bf16_f32 v18, v20, v21
	v_cvt_pk_bf16_f32 v19, v22, v23
	v_cvt_pk_bf16_f32 v20, v24, v25
	v_cvt_pk_bf16_f32 v21, v26, v27
	v_cvt_pk_bf16_f32 v22, v28, v29
	v_cvt_pk_bf16_f32 v23, v30, v31
	v_cvt_pk_bf16_f32 v24, v76, v77
	v_cvt_pk_bf16_f32 v25, v78, v79
	v_lshlrev_b64 v[30:31], 11, v[74:75]
	v_lshl_add_u64 v[30:31], s[34:35], 0, v[30:31]
	v_lshl_add_u64 v[30:31], v[30:31], 0, v[72:73]
	s_nop 0
	v_pk_add_f32 v[80:81], v[4:5], v[0:1]
	v_lshlrev_b32_e32 v0, 16, v105
	v_and_b32_e32 v1, 0xffff0000, v105
	v_pk_fma_f32 v[0:1], v[6:7], v[0:1], 0 op_sel_hi:[1,1,0]
	v_lshlrev_b32_e32 v4, 16, v106
	v_pk_add_f32 v[82:83], v[0:1], v[2:3]
	v_mov_b64_e32 v[0:1], v[224:225]
	v_mov_b64_e32 v[2:3], v[226:227]
	v_and_b32_e32 v5, 0xffff0000, v106
	v_pk_fma_f32 v[4:5], v[8:9], v[4:5], 0 op_sel_hi:[1,1,0]
	v_cvt_pk_bf16_f32 v6, v60, v61
	v_cvt_pk_bf16_f32 v7, v62, v63
	v_cvt_pk_bf16_f32 v8, v48, v49
	v_cvt_pk_bf16_f32 v9, v50, v51
	v_cvt_pk_bf16_f32 v26, v80, v81
	v_cvt_pk_bf16_f32 v27, v82, v83
	s_nop 0
	v_pk_add_f32 v[84:85], v[4:5], v[0:1]
	v_lshlrev_b32_e32 v0, 16, v107
	v_and_b32_e32 v1, 0xffff0000, v107
	v_pk_fma_f32 v[0:1], v[10:11], v[0:1], 0 op_sel_hi:[1,1,0]
	v_lshlrev_b32_e32 v4, 16, v92
	v_pk_add_f32 v[86:87], v[0:1], v[2:3]
	v_mov_b64_e32 v[0:1], v[228:229]
	v_mov_b64_e32 v[2:3], v[230:231]
	v_and_b32_e32 v5, 0xffff0000, v92
	v_pk_fma_f32 v[4:5], v[12:13], v[4:5], 0 op_sel_hi:[1,1,0]
	v_cvt_pk_bf16_f32 v10, v36, v37
	v_cvt_pk_bf16_f32 v11, v38, v39
	v_cvt_pk_bf16_f32 v12, v40, v41
	v_cvt_pk_bf16_f32 v13, v42, v43
	v_cvt_pk_bf16_f32 v28, v84, v85
	v_cvt_pk_bf16_f32 v29, v86, v87
	s_nop 0
	v_pk_add_f32 v[70:71], v[4:5], v[0:1]
	v_lshlrev_b32_e32 v0, 16, v93
	v_and_b32_e32 v1, 0xffff0000, v93
	v_pk_fma_f32 v[0:1], v[14:15], v[0:1], 0 op_sel_hi:[1,1,0]
	v_cvt_pk_bf16_f32 v15, v34, v35
	v_mov_b32_e32 v34, v160
	v_pk_add_f32 v[88:89], v[0:1], v[2:3]
	v_lshrrev_b32_e32 v35, 6, v34
	v_and_b32_e32 v36, 31, v34
	v_mul_lo_u32 v35, v35, s66
	v_lshrrev_b32_e32 v37, 2, v34
	v_add_u32_e32 v35, 0, v35
	v_mul_u32_u24_e32 v36, 0x90, v36
	v_and_b32_e32 v37, 8, v37
	v_cvt_pk_bf16_f32 v0, v66, v67
	v_cvt_pk_bf16_f32 v1, v68, v69
	v_cvt_pk_bf16_f32 v2, v52, v53
	v_cvt_pk_bf16_f32 v3, v54, v55
	v_add3_u32 v36, v35, v36, v37
	v_cvt_pk_bf16_f32 v4, v56, v57
	v_cvt_pk_bf16_f32 v5, v58, v59
	v_cvt_pk_bf16_f32 v14, v32, v33
	s_barrier
; #define TID (opq_v((int)threadIdx.x))
; DEVINL void store_rows_via_lds(unsigned char* lds, const u32x2 (&pk)[2][2][4], bf16_t* out_row0, int ld) {
;     const int tid = TID, lane = tid & 63, w = tid >> 6, r = lane & 31, h = lane >> 5;
;     unsigned char* reg = lds + w * (64 * 144);
;     __syncthreads();
; #pragma unroll
;     for (int mi = 0; mi < 2; ++mi)
; #pragma unroll
;         for (int ni = 0; ni < 2; ++ni)
; #pragma unroll
;             for (int g = 0; g < 4; ++g) *(u32x2*)(reg + (mi * 32 + r) * 144 + (ni * 32 + 8 * g + 4 * h) * 2) = pk[mi][ni][g];
;     __syncthreads();
; #pragma unroll
;     for (int it = 0; it < 8; ++it) {
;         const int idx = it * 64 + lane, row = idx >> 3, c16 = idx & 7;
;         const u32x4 v = *(const u32x4*)(reg + row * 144 + c16 * 16);
;         *(u32x4*)(out_row0 + (size_t)row * ld + c16 * 8) = v;
;     }
; }
	ds_write2_b64 v36, v[0:1], v[2:3] offset1:2
	ds_write2_b64 v36, v[4:5], v[6:7] offset0:4 offset1:6
	ds_write2_b64 v36, v[8:9], v[10:11] offset0:8 offset1:10
	ds_write2_b64 v36, v[12:13], v[16:17] offset0:12 offset1:14
	v_add_u32_e32 v0, 0x1000, v36
	v_cvt_pk_bf16_f32 v32, v70, v71
	v_cvt_pk_bf16_f32 v33, v88, v89
	ds_write2_b64 v0, v[14:15], v[18:19] offset0:64 offset1:66
	ds_write2_b64 v0, v[20:21], v[22:23] offset0:68 offset1:70
	ds_write2_b64 v0, v[24:25], v[26:27] offset0:72 offset1:74
	ds_write2_b64 v0, v[28:29], v[32:33] offset0:76 offset1:78
	v_lshlrev_b32_e32 v0, 4, v34
	v_bfe_u32 v6, v34, 3, 3
	v_and_b32_e32 v64, 0x70, v0
	v_mul_u32_u24_e32 v2, 0x90, v6
	v_add3_u32 v8, v35, v64, v2
	s_waitcnt lgkmcnt(0)
	s_barrier
	ds_read_b128 v[2:5], v8
	v_lshl_add_u64 v[0:1], v[30:31], 0, v[64:65]
	v_lshlrev_b32_e32 v64, 11, v6
	v_lshl_add_u64 v[6:7], v[0:1], 0, v[64:65]
	s_waitcnt lgkmcnt(0)
	global_store_dwordx4 v[6:7], v[2:5], off sc1
	ds_read_b128 v[2:5], v8 offset:1152
	v_or_b32_e32 v6, 0x4000, v64
	v_mov_b32_e32 v7, v65
	v_lshl_add_u64 v[6:7], v[0:1], 0, v[6:7]
	s_waitcnt lgkmcnt(0)
	global_store_dwordx4 v[6:7], v[2:5], off sc1
	ds_read_b128 v[2:5], v8 offset:2304
	v_or_b32_e32 v6, 0x8000, v64
	v_mov_b32_e32 v7, v65
	v_lshl_add_u64 v[6:7], v[0:1], 0, v[6:7]
	s_waitcnt lgkmcnt(0)
	global_store_dwordx4 v[6:7], v[2:5], off sc1
	ds_read_b128 v[2:5], v8 offset:3456
	v_or_b32_e32 v6, 0xc000, v64
	v_mov_b32_e32 v7, v65
	v_lshl_add_u64 v[6:7], v[0:1], 0, v[6:7]
	s_waitcnt lgkmcnt(0)
	global_store_dwordx4 v[6:7], v[2:5], off sc1
	ds_read_b128 v[2:5], v8 offset:4608
	v_or_b32_e32 v6, 0x10000, v64
	v_mov_b32_e32 v7, v65
	v_lshl_add_u64 v[6:7], v[0:1], 0, v[6:7]
	s_waitcnt lgkmcnt(0)
	global_store_dwordx4 v[6:7], v[2:5], off sc1
	ds_read_b128 v[2:5], v8 offset:5760
	v_or_b32_e32 v6, 0x14000, v64
	v_mov_b32_e32 v7, v65
	v_lshl_add_u64 v[6:7], v[0:1], 0, v[6:7]
	s_waitcnt lgkmcnt(0)
	global_store_dwordx4 v[6:7], v[2:5], off sc1
	ds_read_b128 v[2:5], v8 offset:6912
	v_or_b32_e32 v6, 0x18000, v64
	v_mov_b32_e32 v7, v65
	v_lshl_add_u64 v[6:7], v[0:1], 0, v[6:7]
	v_or_b32_e32 v64, 0x1c000, v64
	s_waitcnt lgkmcnt(0)
	global_store_dwordx4 v[6:7], v[2:5], off sc1
	ds_read_b128 v[2:5], v8 offset:8064
	v_lshl_add_u64 v[0:1], v[0:1], 0, v[64:65]
	s_waitcnt lgkmcnt(0)
	global_store_dwordx4 v[0:1], v[2:5], off sc1
	s_cbranch_scc0 .LBB0_89

;     DEVINL bf16_t* Z() const { return (bf16_t*)(ws + OFF_Z); }
; #define TID (opq_v((int)threadIdx.x))
; DEVINL unsigned cvt_pk_bf16(float lo, float hi) { const f32x2 v = {lo, hi}; return __builtin_bit_cast(unsigned, __builtin_convertvector(v, bf16x2v)); }
; DEVINL void store_rows_via_lds(unsigned char* lds, const u32x2 (&pk)[2][2][4], bf16_t* out_row0, int ld) {
;     const int tid = TID, lane = tid & 63, w = tid >> 6, r = lane & 31, h = lane >> 5;
;     unsigned char* reg = lds + w * (64 * 144);
;     __syncthreads();
; #pragma unroll
;     for (int mi = 0; mi < 2; ++mi)
; #pragma unroll
;         for (int ni = 0; ni < 2; ++ni)
; #pragma unroll
;             for (int g = 0; g < 4; ++g) *(u32x2*)(reg + (mi * 32 + r) * 144 + (ni * 32 + 8 * g + 4 * h) * 2) = pk[mi][ni][g];
;     __syncthreads();
; #pragma unroll
;     for (int it = 0; it < 8; ++it) {
;         const int idx = it * 64 + lane, row = idx >> 3, c16 = idx & 7;
;         const u32x4 v = *(const u32x4*)(reg + row * 144 + c16 * 16);
;         *(u32x4*)(out_row0 + (size_t)row * ld + c16 * 8) = v;
;     }
; }
; DEVINL void epi_inproj(const Ctx& c, int layer, f32x16 (&acc)[2][2], int mbase, int nbase, unsigned char* lds) {
;     ...
;                 { u32x2 o; o[0] = cvt_pk_bf16(v[0], v[1]); o[1] = cvt_pk_bf16(v[2], v[3]); pkz[mi][ni][g] = o; }
;             }
;     }
;     if (zc >= 0) store_rows_via_lds(lds, pkz, c.Z() + (size_t)mbase * ZW + zc, ZW);
.LBB0_536:
	s_or_b64 exec, exec, s[6:7]
	v_cvt_pk_bf16_f32 v0, v24, v25
	v_cvt_pk_bf16_f32 v1, v26, v27
	v_cvt_pk_bf16_f32 v2, v20, v21
	v_cvt_pk_bf16_f32 v3, v22, v23
	v_cvt_pk_bf16_f32 v4, v16, v17
	v_cvt_pk_bf16_f32 v5, v18, v19
	v_cvt_pk_bf16_f32 v6, v46, v47
	v_cvt_pk_bf16_f32 v7, v90, v91
	v_cvt_pk_bf16_f32 v8, v42, v43
	v_cvt_pk_bf16_f32 v9, v44, v45
	v_cvt_pk_bf16_f32 v10, v38, v39
	v_cvt_pk_bf16_f32 v11, v40, v41
	v_cvt_pk_bf16_f32 v12, v32, v33
	v_cvt_pk_bf16_f32 v13, v34, v35
	v_cvt_pk_bf16_f32 v14, v60, v61
	v_cvt_pk_bf16_f32 v15, v62, v63
	v_cvt_pk_bf16_f32 v18, v56, v57
	v_cvt_pk_bf16_f32 v19, v58, v59
	v_cvt_pk_bf16_f32 v20, v52, v53
	v_cvt_pk_bf16_f32 v21, v54, v55
	v_cvt_pk_bf16_f32 v22, v48, v49
	v_cvt_pk_bf16_f32 v23, v50, v51
	v_cvt_pk_bf16_f32 v24, v86, v87
	v_cvt_pk_bf16_f32 v25, v88, v89
	v_cvt_pk_bf16_f32 v26, v82, v83
	v_cvt_pk_bf16_f32 v27, v84, v85
	v_cvt_pk_bf16_f32 v32, v78, v79
	v_cvt_pk_bf16_f32 v33, v80, v81
	v_cvt_pk_bf16_f32 v34, v74, v75
	v_cvt_pk_bf16_f32 v35, v76, v77
	v_or_b32_e32 v36, s36, v73
	v_cvt_pk_bf16_f32 v16, v28, v29
	v_cvt_pk_bf16_f32 v17, v30, v31
	v_cmp_lt_i32_e32 vcc, -1, v66
	s_and_saveexec_b64 s[6:7], vcc
	s_cbranch_execz .LBB0_538
	v_readlane_b32 s8, v247, 7
	v_readlane_b32 s9, v247, 8
	v_mov_b32_e32 v30, v160
	s_waitcnt vmcnt(0)
	v_mov_b64_e32 v[28:29], s[8:9]
	v_mad_i64_i32 v[28:29], s[8:9], v36, s49, v[28:29]
	v_lshrrev_b32_e32 v31, 6, v30
	s_movk_i32 s8, 0x2400
	v_and_b32_e32 v37, 31, v30
	v_mul_lo_u32 v31, v31, s8
	v_lshrrev_b32_e32 v38, 2, v30
	v_add_u32_e32 v31, 0, v31
	v_mul_u32_u24_e32 v37, 0x90, v37
	v_and_b32_e32 v38, 8, v38
	v_add3_u32 v37, v31, v37, v38
	s_barrier
	ds_write2_b64 v37, v[34:35], v[32:33] offset1:2
	ds_write2_b64 v37, v[26:27], v[24:25] offset0:4 offset1:6
	ds_write2_b64 v37, v[22:23], v[20:21] offset0:8 offset1:10
	ds_write2_b64 v37, v[18:19], v[14:15] offset0:12 offset1:14
	v_add_u32_e32 v37, 0x1000, v37
	v_mov_b32_e32 v67, v65
	ds_write2_b64 v37, v[12:13], v[10:11] offset0:64 offset1:66
	ds_write2_b64 v37, v[8:9], v[6:7] offset0:68 offset1:70
	ds_write2_b64 v37, v[4:5], v[2:3] offset0:72 offset1:74
	ds_write2_b64 v37, v[0:1], v[16:17] offset0:76 offset1:78
	v_lshlrev_b32_e32 v37, 4, v30
	v_lshl_add_u64 v[28:29], v[66:67], 1, v[28:29]
	v_and_b32_e32 v64, 0x70, v37
	v_bfe_u32 v37, v30, 3, 3
	v_lshl_add_u64 v[42:43], v[28:29], 0, v[64:65]
	v_mul_u32_u24_e32 v28, 0x90, v37
	v_add3_u32 v48, v31, v64, v28
	s_waitcnt lgkmcnt(0)
	s_barrier
	ds_read_b128 v[28:31], v48
	ds_read_b128 v[38:41], v48 offset:1152
	v_mul_u32_u24_e32 v37, 0x2200, v37
	v_lshlrev_b32_e32 v64, 1, v37
	v_lshl_add_u64 v[44:45], v[42:43], 0, v[64:65]
	s_mov_b32 s8, 0x22000
	s_waitcnt lgkmcnt(1)
	global_store_dwordx4 v[44:45], v[28:31], off sc1
	s_nop 1
	v_add_co_u32_e32 v28, vcc, s8, v44
	s_mov_b32 s8, 0x44000
	s_nop 0
	v_addc_co_u32_e32 v29, vcc, 0, v45, vcc
	s_waitcnt lgkmcnt(0)
	global_store_dwordx4 v[28:29], v[38:41], off sc1
	ds_read_b128 v[28:31], v48 offset:2304
	ds_read_b128 v[38:41], v48 offset:3456
	v_add_co_u32_e32 v46, vcc, s8, v44
	s_mov_b32 s8, 0x66000
	s_nop 0
	v_addc_co_u32_e32 v47, vcc, 0, v45, vcc
	s_waitcnt lgkmcnt(1)
	global_store_dwordx4 v[46:47], v[28:31], off sc1
	s_nop 1
	v_add_co_u32_e32 v28, vcc, s8, v44
	s_mov_b32 s8, 0x88000
	s_nop 0
	v_addc_co_u32_e32 v29, vcc, 0, v45, vcc
	s_waitcnt lgkmcnt(0)
	global_store_dwordx4 v[28:29], v[38:41], off sc1
	ds_read_b128 v[28:31], v48 offset:4608
	ds_read_b128 v[38:41], v48 offset:5760
	v_add_co_u32_e32 v44, vcc, s8, v44
	s_nop 1
	v_addc_co_u32_e32 v45, vcc, 0, v45, vcc
	s_waitcnt lgkmcnt(1)
	global_store_dwordx4 v[44:45], v[28:31], off sc1
	v_add_u32_e32 v44, 0xcc000, v64
	v_mov_b32_e32 v45, v65
	v_add_u32_e32 v28, 0xaa000, v64
	v_mov_b32_e32 v29, v65
	v_lshl_add_u64 v[28:29], v[42:43], 0, v[28:29]
	s_waitcnt lgkmcnt(0)
	global_store_dwordx4 v[28:29], v[38:41], off sc1
	ds_read_b128 v[28:31], v48 offset:6912
	ds_read_b128 v[38:41], v48 offset:8064
	v_lshl_add_u64 v[44:45], v[42:43], 0, v[44:45]
	v_add_u32_e32 v64, 0xee000, v64
	s_waitcnt lgkmcnt(1)
	global_store_dwordx4 v[44:45], v[28:31], off sc1
	s_nop 1
	v_lshl_add_u64 v[28:29], v[42:43], 0, v[64:65]
	s_waitcnt lgkmcnt(0)
	global_store_dwordx4 v[28:29], v[38:41], off sc1
	s_or_b64 exec, exec, s[6:7]
	v_cmp_ne_u64_e32 vcc, 0, v[68:69]
	s_and_saveexec_b64 s[6:7], vcc
	s_cbranch_execz .LBB0_363
	s_branch .LBB0_539

; #define TID (opq_v((int)threadIdx.x))
; DEVINL void store_cols_via_lds(unsigned char* lds, const u32x2 (&pk)[2][2][4], bf16_t* vt_col0  ) {
;     const int tid = TID, lane = tid & 63, w = tid >> 6, r = lane & 31, h = lane >> 5;
;     unsigned char* reg = lds + w * (64 * 144);
;     __syncthreads();
; #pragma unroll
;     for (int mi = 0; mi < 2; ++mi)
; #pragma unroll
;         for (int ni = 0; ni < 2; ++ni)
; #pragma unroll
;             for (int g = 0; g < 4; ++g) {
;                 const int n = ni * 32 + 8 * g + 4 * h, m = mi * 32 + r;
;                 *(bf16_t*)(reg + (n + 0) * 144 + m * 2) = (bf16_t)(pk[mi][ni][g][0] & 0xffffu);
;                 *(bf16_t*)(reg + (n + 1) * 144 + m * 2) = (bf16_t)(pk[mi][ni][g][0] >> 16);
;                 *(bf16_t*)(reg + (n + 2) * 144 + m * 2) = (bf16_t)(pk[mi][ni][g][1] & 0xffffu);
;                 *(bf16_t*)(reg + (n + 3) * 144 + m * 2) = (bf16_t)(pk[mi][ni][g][1] >> 16);
;             }
;     __syncthreads();
; #pragma unroll
;     for (int it = 0; it < 8; ++it) {
;         const int idx = it * 64 + lane, n = idx >> 3, c16 = idx & 7;
;         const u32x4 v = *(const u32x4*)(reg + n * 144 + c16 * 16);
;         *(u32x4*)(vt_col0 + (size_t)n * L + c16 * 8) = v;
;     }
; }
; DEVINL void epi_inproj(const Ctx& c, int layer, f32x16 (&acc)[2][2], int mbase, int nbase, unsigned char* lds) {
;     ...
;     if (vt) { const int b0 = mbase / L, p0 = mbase - b0 * L; store_cols_via_lds(lds, pkz, vt + ((size_t)(b0 * vC + vcol)) * L + p0); }
.LBB0_539:
	s_mov_b32 s8, 0x78787879
	v_mul_hi_i32 v28, v36, s8
	v_lshrrev_b32_e32 v29, 31, v28
	v_ashrrev_i32_e32 v28, 10, v28
	v_add_u32_e32 v29, v28, v29
	s_movk_i32 s8, 0xf780
	v_mad_i32_i24 v28, v29, s8, v36
	v_mad_i32_i24 v29, v94, v29, v93
	s_movk_i32 s8, 0x1100
	v_mad_i64_i32 v[30:31], s[8:9], v29, s8, v[68:69]
	v_ashrrev_i32_e32 v29, 31, v28
	v_lshl_add_u64 v[28:29], v[28:29], 1, v[30:31]
	v_mov_b32_e32 v30, v160
	s_movk_i32 s8, 0x2400
	v_lshrrev_b32_e32 v31, 6, v30
	v_lshrrev_b32_e32 v36, 3, v30
	v_mul_lo_u32 v31, v31, s8
	v_and_b32_e32 v36, 4, v36
	v_lshlrev_b32_e32 v37, 1, v30
	v_add_u32_e32 v31, 0, v31
	v_and_b32_e32 v37, 62, v37
	v_mul_u32_u24_e32 v36, 0x90, v36
	v_add3_u32 v36, v31, v36, v37
	s_waitcnt vmcnt(0)
	s_barrier
	ds_write_b16 v36, v34
	ds_write_b16_d16_hi v36, v34 offset:144
	ds_write_b16 v36, v35 offset:288
	ds_write_b16_d16_hi v36, v35 offset:432
	ds_write_b16 v36, v32 offset:1152
	ds_write_b16_d16_hi v36, v32 offset:1296
	ds_write_b16 v36, v33 offset:1440
	ds_write_b16_d16_hi v36, v33 offset:1584
	ds_write_b16 v36, v26 offset:2304
	ds_write_b16_d16_hi v36, v26 offset:2448
	ds_write_b16 v36, v27 offset:2592
	ds_write_b16_d16_hi v36, v27 offset:2736
	ds_write_b16 v36, v24 offset:3456
	ds_write_b16_d16_hi v36, v24 offset:3600
	ds_write_b16 v36, v25 offset:3744
	ds_write_b16_d16_hi v36, v25 offset:3888
	ds_write_b16 v36, v22 offset:4608
	ds_write_b16_d16_hi v36, v22 offset:4752
	ds_write_b16 v36, v23 offset:4896
	ds_write_b16_d16_hi v36, v23 offset:5040
	ds_write_b16 v36, v20 offset:5760
	ds_write_b16_d16_hi v36, v20 offset:5904
	ds_write_b16 v36, v21 offset:6048
	ds_write_b16_d16_hi v36, v21 offset:6192
	ds_write_b16 v36, v18 offset:6912
	ds_write_b16_d16_hi v36, v18 offset:7056
	ds_write_b16 v36, v19 offset:7200
	ds_write_b16_d16_hi v36, v19 offset:7344
	ds_write_b16 v36, v14 offset:8064
	ds_write_b16_d16_hi v36, v14 offset:8208
	ds_write_b16 v36, v15 offset:8352
	ds_write_b16_d16_hi v36, v15 offset:8496
	ds_write_b16 v36, v12 offset:64
	ds_write_b16_d16_hi v36, v12 offset:208
	ds_write_b16 v36, v13 offset:352
	ds_write_b16_d16_hi v36, v13 offset:496
	ds_write_b16 v36, v10 offset:1216
	ds_write_b16_d16_hi v36, v10 offset:1360
	ds_write_b16 v36, v11 offset:1504
	ds_write_b16_d16_hi v36, v11 offset:1648
	ds_write_b16 v36, v8 offset:2368
	ds_write_b16_d16_hi v36, v8 offset:2512
	ds_write_b16 v36, v9 offset:2656
	ds_write_b16_d16_hi v36, v9 offset:2800
	ds_write_b16 v36, v6 offset:3520
	ds_write_b16_d16_hi v36, v6 offset:3664
	ds_write_b16 v36, v7 offset:3808
	ds_write_b16_d16_hi v36, v7 offset:3952
	ds_write_b16 v36, v4 offset:4672
	ds_write_b16_d16_hi v36, v4 offset:4816
	ds_write_b16 v36, v5 offset:4960
	ds_write_b16_d16_hi v36, v5 offset:5104
	ds_write_b16 v36, v2 offset:5824
	ds_write_b16_d16_hi v36, v2 offset:5968
	ds_write_b16 v36, v3 offset:6112
	ds_write_b16_d16_hi v36, v3 offset:6256
	ds_write_b16 v36, v0 offset:6976
	ds_write_b16_d16_hi v36, v0 offset:7120
	ds_write_b16 v36, v1 offset:7264
	ds_write_b16_d16_hi v36, v1 offset:7408
	ds_write_b16 v36, v16 offset:8128
	ds_write_b16_d16_hi v36, v16 offset:8272
	ds_write_b16 v36, v17 offset:8416
	ds_write_b16_d16_hi v36, v17 offset:8560
	v_lshlrev_b32_e32 v0, 4, v30
	v_bfe_u32 v4, v30, 3, 3
	v_and_b32_e32 v64, 0x70, v0
	v_mul_u32_u24_e32 v0, 0x90, v4
	v_add3_u32 v14, v31, v64, v0
	s_waitcnt lgkmcnt(0)
	s_barrier
	ds_read_b128 v[0:3], v14
	v_mul_u32_u24_e32 v4, 0x880, v4
	v_lshl_add_u64 v[8:9], v[28:29], 0, v[64:65]
	v_lshlrev_b32_e32 v64, 1, v4
	ds_read_b128 v[4:7], v14 offset:1152
	v_lshl_add_u64 v[10:11], v[8:9], 0, v[64:65]
	s_mov_b32 s8, 0x8000
	s_waitcnt lgkmcnt(1)
	global_store_dwordx4 v[10:11], v[0:3], off sc1
	s_nop 1
	v_add_co_u32_e32 v0, vcc, s8, v10
	s_mov_b32 s8, 0x11000
	s_nop 0
	v_addc_co_u32_e32 v1, vcc, 0, v11, vcc
	s_waitcnt lgkmcnt(0)
	global_store_dwordx4 v[0:1], v[4:7], off offset:2048 sc1
	ds_read_b128 v[0:3], v14 offset:2304
	ds_read_b128 v[4:7], v14 offset:3456
	v_add_co_u32_e32 v12, vcc, s8, v10
	s_mov_b32 s8, 0x19000
	s_nop 0
	v_addc_co_u32_e32 v13, vcc, 0, v11, vcc
	s_waitcnt lgkmcnt(1)
	global_store_dwordx4 v[12:13], v[0:3], off sc1
	s_nop 1
	v_add_co_u32_e32 v0, vcc, s8, v10
	s_mov_b32 s8, 0x22000
	s_nop 0
	v_addc_co_u32_e32 v1, vcc, 0, v11, vcc
	s_waitcnt lgkmcnt(0)
	global_store_dwordx4 v[0:1], v[4:7], off offset:2048 sc1
	ds_read_b128 v[0:3], v14 offset:4608
	ds_read_b128 v[4:7], v14 offset:5760
	v_add_co_u32_e32 v10, vcc, s8, v10
	s_nop 1
	v_addc_co_u32_e32 v11, vcc, 0, v11, vcc
	s_waitcnt lgkmcnt(1)
	global_store_dwordx4 v[10:11], v[0:3], off sc1
	v_add_u32_e32 v10, 0x33000, v64
	v_mov_b32_e32 v11, v65
	v_add_u32_e32 v0, 0x2a800, v64
	v_mov_b32_e32 v1, v65
	v_lshl_add_u64 v[0:1], v[8:9], 0, v[0:1]
	s_waitcnt lgkmcnt(0)
	global_store_dwordx4 v[0:1], v[4:7], off sc1
	ds_read_b128 v[0:3], v14 offset:6912
	ds_read_b128 v[4:7], v14 offset:8064
	v_lshl_add_u64 v[10:11], v[8:9], 0, v[10:11]
	v_add_u32_e32 v64, 0x3b800, v64
	s_waitcnt lgkmcnt(1)
	global_store_dwordx4 v[10:11], v[0:3], off sc1
	s_nop 1
	v_lshl_add_u64 v[0:1], v[8:9], 0, v[64:65]
	s_waitcnt lgkmcnt(0)
	global_store_dwordx4 v[0:1], v[4:7], off sc1
	s_branch .LBB0_363
